# mlaproj UQ items rewritten by hand: 128 rows x two n-tiles sharing the CQ tile and its row rstd, rolled 3-stage K-loop, hand-written scale+rope epilogue (same op order), batched QF stores; 792 items i
# speedup vs baseline: 1.0095x; 1.0004x over previous
.Luq:
	s_cmpk_gt_i32 s24, 0x317
	s_cbranch_scc1 .LBB0_314
	s_and_b32 s1, s24, 7
	s_lshr_b32 s2, s24, 3
	s_mul_hi_u32 s0, s2, 0x55555556
	s_mul_i32 s19, s0, 3
	s_sub_i32 s19, s2, s19
	s_lshl_b32 s0, s0, 3
	s_or_b32 s1, s0, s1
	s_lshl_b32 s25, s1, 7
	v_readlane_b32 s48, v225, 48
	v_readlane_b32 s49, v225, 49
	s_nop 1
	s_lshl_b32 s0, s25, 10
	s_add_u32 s10, s48, 0xac7c000
	s_addc_u32 s11, s49, 0
	s_add_u32 s10, s10, s0
	s_addc_u32 s11, s11, 0
	s_lshl_b32 s0, s19, 18
	s_add_u32 s12, s59, s0
	v_readlane_b32 s13, v225, 54
	s_addc_u32 s13, s13, 0
	s_add_u32 s12, s12, 0xbc0000
	s_addc_u32 s13, s13, 0
	s_add_u32 s14, s12, 0x20000
	s_addc_u32 s15, s13, 0
	s_mul_i32 s18, s25, 0x600
	s_lshl_b32 s0, s19, 9
	s_add_i32 s18, s18, s0
	s_cmp_ge_u32 s25, 0x8000
	s_cselect_b32 s27, 1, 0
	s_and_b32 s26, s25, 0x1fff
	s_lshr_b32 s26, s26, 6
	s_movk_i32 s2, 0x1320
	v_lshrrev_b32_e32 v0, 2, v196
	v_and_b32_e32 v0, 12, v0
	v_lshrrev_b32_e64 v0, v0, s2
	v_xor_b32_e32 v0, v0, v196
	v_and_b32_e32 v0, 3, v0
	v_lshlrev_b32_e32 v0, 4, v0
	v_lshrrev_b32_e32 v2, 2, v196
	v_lshl_add_u32 v2, v2, 10, v0
	v_add_u32_e32 v3, 0x10000, v2
	v_and_b32_e32 v213, 15, v196
	v_and_b32_e32 v214, 12, v213
	v_lshrrev_b32_e64 v214, v214, s2
	v_and_b32_e32 v214, 3, v214
	v_bfe_u32 v215, v196, 4, 2
	v_xor_b32_e32 v214, v214, v215
	v_lshlrev_b32_e32 v214, 4, v214
	v_lshl_add_u32 v214, v213, 6, v214
	v_lshrrev_b32_e32 v213, 7, v196
	v_lshl_add_u32 v64, v213, 12, v214
	v_bfe_u32 v213, v196, 6, 1
	v_lshl_add_u32 v65, v213, 12, v214
	v_readfirstlane_b32 s16, v196
	s_lshl_b32 s16, s16, 4
	s_mov_b32 m0, s16
	s_nop 0
	global_load_lds_dwordx4 v2, s[10:11]
	s_add_i32 m0, s16, 0x1000
	s_nop 0
	global_load_lds_dwordx4 v3, s[10:11]
	s_add_i32 m0, s16, 0x2000
	s_nop 0
	global_load_lds_dwordx4 v2, s[12:13]
	s_add_i32 m0, s16, 0x3000
	s_nop 0
	global_load_lds_dwordx4 v3, s[12:13]
	s_add_i32 m0, s16, 0x4000
	s_nop 0
	global_load_lds_dwordx4 v2, s[14:15]
	s_add_i32 m0, s16, 0x5000
	s_nop 0
	global_load_lds_dwordx4 v3, s[14:15]
	v_add_u32_e32 v2, 64, v2
	v_add_u32_e32 v3, 64, v3
	s_add_i32 m0, s16, 0x6000
	s_nop 0
	global_load_lds_dwordx4 v2, s[10:11]
	s_add_i32 m0, s16, 0x7000
	s_nop 0
	global_load_lds_dwordx4 v3, s[10:11]
	s_add_i32 m0, s16, 0x8000
	s_nop 0
	global_load_lds_dwordx4 v2, s[12:13]
	s_add_i32 m0, s16, 0x9000
	s_nop 0
	global_load_lds_dwordx4 v3, s[12:13]
	s_add_i32 m0, s16, 0xa000
	s_nop 0
	global_load_lds_dwordx4 v2, s[14:15]
	s_add_i32 m0, s16, 0xb000
	s_nop 0
	global_load_lds_dwordx4 v3, s[14:15]
	v_add_u32_e32 v2, 64, v2
	v_add_u32_e32 v3, 64, v3
	v_lshlrev_b32_e32 v213, 9, v196
	global_load_dwordx4 v[4:7], v213, s[10:11]
	global_load_dwordx4 v[8:11], v213, s[10:11] offset:16
	global_load_dwordx4 v[12:15], v213, s[10:11] offset:32
	global_load_dwordx4 v[16:19], v213, s[10:11] offset:48
	global_load_dwordx4 v[20:23], v213, s[10:11] offset:64
	global_load_dwordx4 v[24:27], v213, s[10:11] offset:80
	global_load_dwordx4 v[28:31], v213, s[10:11] offset:96
	global_load_dwordx4 v[32:35], v213, s[10:11] offset:112
	global_load_dwordx4 v[36:39], v213, s[10:11] offset:128
	global_load_dwordx4 v[40:43], v213, s[10:11] offset:144
	global_load_dwordx4 v[44:47], v213, s[10:11] offset:160
	global_load_dwordx4 v[48:51], v213, s[10:11] offset:176
	global_load_dwordx4 v[52:55], v213, s[10:11] offset:192
	global_load_dwordx4 v[56:59], v213, s[10:11] offset:208
	global_load_dwordx4 v[60:63], v213, s[10:11] offset:224
	global_load_dwordx4 v[72:75], v213, s[10:11] offset:240
	global_load_dwordx4 v[76:79], v213, s[10:11] offset:256
	global_load_dwordx4 v[80:83], v213, s[10:11] offset:272
	global_load_dwordx4 v[84:87], v213, s[10:11] offset:288
	global_load_dwordx4 v[144:147], v213, s[10:11] offset:304
	global_load_dwordx4 v[148:151], v213, s[10:11] offset:320
	global_load_dwordx4 v[152:155], v213, s[10:11] offset:336
	global_load_dwordx4 v[156:159], v213, s[10:11] offset:352
	global_load_dwordx4 v[160:163], v213, s[10:11] offset:368
	global_load_dwordx4 v[164:167], v213, s[10:11] offset:384
	global_load_dwordx4 v[168:171], v213, s[10:11] offset:400
	global_load_dwordx4 v[172:175], v213, s[10:11] offset:416
	global_load_dwordx4 v[176:179], v213, s[10:11] offset:432
	global_load_dwordx4 v[180:183], v213, s[10:11] offset:448
	global_load_dwordx4 v[184:187], v213, s[10:11] offset:464
	global_load_dwordx4 v[188:191], v213, s[10:11] offset:480
	global_load_dwordx4 v[192:195], v213, s[10:11] offset:496
	v_mov_b32_e32 v71, 0
	s_waitcnt vmcnt(31)
	v_lshlrev_b32_e32 v240, 16, v4
	v_and_b32_e32 v241, 0xffff0000, v4
	v_pk_mul_f32 v[240:241], v[240:241], v[240:241]
	v_and_b32_e32 v243, 0xffff0000, v6
	v_add_f32_e32 v244, v240, v241
	v_and_b32_e32 v242, 0xffff0000, v5
	v_add_f32_e32 v71, v71, v244
	v_lshlrev_b32_e32 v241, 16, v6
	v_lshlrev_b32_e32 v240, 16, v5
	v_pk_mul_f32 v[244:245], v[242:243], v[242:243]
	s_nop 0
	v_pk_fma_f32 v[244:245], v[240:241], v[240:241], v[244:245]
	s_nop 0
	v_add_f32_e32 v71, v71, v244
	v_add_f32_e32 v71, v71, v245
	v_lshlrev_b32_e32 v240, 16, v7
	v_and_b32_e32 v241, 0xffff0000, v7
	v_pk_mul_f32 v[240:241], v[240:241], v[240:241]
	s_nop 0
	v_add_f32_e32 v240, v240, v241
	v_add_f32_e32 v71, v71, v240
	s_waitcnt vmcnt(30)
	v_lshlrev_b32_e32 v240, 16, v8
	v_and_b32_e32 v241, 0xffff0000, v8
	v_pk_mul_f32 v[240:241], v[240:241], v[240:241]
	v_and_b32_e32 v243, 0xffff0000, v10
	v_add_f32_e32 v244, v240, v241
	v_and_b32_e32 v242, 0xffff0000, v9
	v_add_f32_e32 v71, v71, v244
	v_lshlrev_b32_e32 v241, 16, v10
	v_lshlrev_b32_e32 v240, 16, v9
	v_pk_mul_f32 v[244:245], v[242:243], v[242:243]
	s_nop 0
	v_pk_fma_f32 v[244:245], v[240:241], v[240:241], v[244:245]
	s_nop 0
	v_add_f32_e32 v71, v71, v244
	v_add_f32_e32 v71, v71, v245
	v_lshlrev_b32_e32 v240, 16, v11
	v_and_b32_e32 v241, 0xffff0000, v11
	v_pk_mul_f32 v[240:241], v[240:241], v[240:241]
	s_nop 0
	v_add_f32_e32 v240, v240, v241
	v_add_f32_e32 v71, v71, v240
	s_waitcnt vmcnt(29)
	v_lshlrev_b32_e32 v240, 16, v12
	v_and_b32_e32 v241, 0xffff0000, v12
	v_pk_mul_f32 v[240:241], v[240:241], v[240:241]
	v_and_b32_e32 v243, 0xffff0000, v14
	v_add_f32_e32 v244, v240, v241
	v_and_b32_e32 v242, 0xffff0000, v13
	v_add_f32_e32 v71, v71, v244
	v_lshlrev_b32_e32 v241, 16, v14
	v_lshlrev_b32_e32 v240, 16, v13
	v_pk_mul_f32 v[244:245], v[242:243], v[242:243]
	s_nop 0
	v_pk_fma_f32 v[244:245], v[240:241], v[240:241], v[244:245]
	s_nop 0
	v_add_f32_e32 v71, v71, v244
	v_add_f32_e32 v71, v71, v245
	v_lshlrev_b32_e32 v240, 16, v15
	v_and_b32_e32 v241, 0xffff0000, v15
	v_pk_mul_f32 v[240:241], v[240:241], v[240:241]
	s_nop 0
	v_add_f32_e32 v240, v240, v241
	v_add_f32_e32 v71, v71, v240
	s_waitcnt vmcnt(28)
	v_lshlrev_b32_e32 v240, 16, v16
	v_and_b32_e32 v241, 0xffff0000, v16
	v_pk_mul_f32 v[240:241], v[240:241], v[240:241]
	v_and_b32_e32 v243, 0xffff0000, v18
	v_add_f32_e32 v244, v240, v241
	v_and_b32_e32 v242, 0xffff0000, v17
	v_add_f32_e32 v71, v71, v244
	v_lshlrev_b32_e32 v241, 16, v18
	v_lshlrev_b32_e32 v240, 16, v17
	v_pk_mul_f32 v[244:245], v[242:243], v[242:243]
	s_nop 0
	v_pk_fma_f32 v[244:245], v[240:241], v[240:241], v[244:245]
	s_nop 0
	v_add_f32_e32 v71, v71, v244
	v_add_f32_e32 v71, v71, v245
	v_lshlrev_b32_e32 v240, 16, v19
	v_and_b32_e32 v241, 0xffff0000, v19
	v_pk_mul_f32 v[240:241], v[240:241], v[240:241]
	s_nop 0
	v_add_f32_e32 v240, v240, v241
	v_add_f32_e32 v71, v71, v240
	s_waitcnt vmcnt(27)
	v_lshlrev_b32_e32 v240, 16, v20
	v_and_b32_e32 v241, 0xffff0000, v20
	v_pk_mul_f32 v[240:241], v[240:241], v[240:241]
	v_and_b32_e32 v243, 0xffff0000, v22
	v_add_f32_e32 v244, v240, v241
	v_and_b32_e32 v242, 0xffff0000, v21
	v_add_f32_e32 v71, v71, v244
	v_lshlrev_b32_e32 v241, 16, v22
	v_lshlrev_b32_e32 v240, 16, v21
	v_pk_mul_f32 v[244:245], v[242:243], v[242:243]
	s_nop 0
	v_pk_fma_f32 v[244:245], v[240:241], v[240:241], v[244:245]
	s_nop 0
	v_add_f32_e32 v71, v71, v244
	v_add_f32_e32 v71, v71, v245
	v_lshlrev_b32_e32 v240, 16, v23
	v_and_b32_e32 v241, 0xffff0000, v23
	v_pk_mul_f32 v[240:241], v[240:241], v[240:241]
	s_nop 0
	v_add_f32_e32 v240, v240, v241
	v_add_f32_e32 v71, v71, v240
	s_waitcnt vmcnt(26)
	v_lshlrev_b32_e32 v240, 16, v24
	v_and_b32_e32 v241, 0xffff0000, v24
	v_pk_mul_f32 v[240:241], v[240:241], v[240:241]
	v_and_b32_e32 v243, 0xffff0000, v26
	v_add_f32_e32 v244, v240, v241
	v_and_b32_e32 v242, 0xffff0000, v25
	v_add_f32_e32 v71, v71, v244
	v_lshlrev_b32_e32 v241, 16, v26
	v_lshlrev_b32_e32 v240, 16, v25
	v_pk_mul_f32 v[244:245], v[242:243], v[242:243]
	s_nop 0
	v_pk_fma_f32 v[244:245], v[240:241], v[240:241], v[244:245]
	s_nop 0
	v_add_f32_e32 v71, v71, v244
	v_add_f32_e32 v71, v71, v245
	v_lshlrev_b32_e32 v240, 16, v27
	v_and_b32_e32 v241, 0xffff0000, v27
	v_pk_mul_f32 v[240:241], v[240:241], v[240:241]
	s_nop 0
	v_add_f32_e32 v240, v240, v241
	v_add_f32_e32 v71, v71, v240
	s_waitcnt vmcnt(25)
	v_lshlrev_b32_e32 v240, 16, v28
	v_and_b32_e32 v241, 0xffff0000, v28
	v_pk_mul_f32 v[240:241], v[240:241], v[240:241]
	v_and_b32_e32 v243, 0xffff0000, v30
	v_add_f32_e32 v244, v240, v241
	v_and_b32_e32 v242, 0xffff0000, v29
	v_add_f32_e32 v71, v71, v244
	v_lshlrev_b32_e32 v241, 16, v30
	v_lshlrev_b32_e32 v240, 16, v29
	v_pk_mul_f32 v[244:245], v[242:243], v[242:243]
	s_nop 0
	v_pk_fma_f32 v[244:245], v[240:241], v[240:241], v[244:245]
	s_nop 0
	v_add_f32_e32 v71, v71, v244
	v_add_f32_e32 v71, v71, v245
	v_lshlrev_b32_e32 v240, 16, v31
	v_and_b32_e32 v241, 0xffff0000, v31
	v_pk_mul_f32 v[240:241], v[240:241], v[240:241]
	s_nop 0
	v_add_f32_e32 v240, v240, v241
	v_add_f32_e32 v71, v71, v240
	s_waitcnt vmcnt(24)
	v_lshlrev_b32_e32 v240, 16, v32
	v_and_b32_e32 v241, 0xffff0000, v32
	v_pk_mul_f32 v[240:241], v[240:241], v[240:241]
	v_and_b32_e32 v243, 0xffff0000, v34
	v_add_f32_e32 v244, v240, v241
	v_and_b32_e32 v242, 0xffff0000, v33
	v_add_f32_e32 v71, v71, v244
	v_lshlrev_b32_e32 v241, 16, v34
	v_lshlrev_b32_e32 v240, 16, v33
	v_pk_mul_f32 v[244:245], v[242:243], v[242:243]
	s_nop 0
	v_pk_fma_f32 v[244:245], v[240:241], v[240:241], v[244:245]
	s_nop 0
	v_add_f32_e32 v71, v71, v244
	v_add_f32_e32 v71, v71, v245
	v_lshlrev_b32_e32 v240, 16, v35
	v_and_b32_e32 v241, 0xffff0000, v35
	v_pk_mul_f32 v[240:241], v[240:241], v[240:241]
	s_nop 0
	v_add_f32_e32 v240, v240, v241
	v_add_f32_e32 v71, v71, v240
	s_waitcnt vmcnt(23)
	v_lshlrev_b32_e32 v240, 16, v36
	v_and_b32_e32 v241, 0xffff0000, v36
	v_pk_mul_f32 v[240:241], v[240:241], v[240:241]
	v_and_b32_e32 v243, 0xffff0000, v38
	v_add_f32_e32 v244, v240, v241
	v_and_b32_e32 v242, 0xffff0000, v37
	v_add_f32_e32 v71, v71, v244
	v_lshlrev_b32_e32 v241, 16, v38
	v_lshlrev_b32_e32 v240, 16, v37
	v_pk_mul_f32 v[244:245], v[242:243], v[242:243]
	s_nop 0
	v_pk_fma_f32 v[244:245], v[240:241], v[240:241], v[244:245]
	s_nop 0
	v_add_f32_e32 v71, v71, v244
	v_add_f32_e32 v71, v71, v245
	v_lshlrev_b32_e32 v240, 16, v39
	v_and_b32_e32 v241, 0xffff0000, v39
	v_pk_mul_f32 v[240:241], v[240:241], v[240:241]
	s_nop 0
	v_add_f32_e32 v240, v240, v241
	v_add_f32_e32 v71, v71, v240
	s_waitcnt vmcnt(22)
	v_lshlrev_b32_e32 v240, 16, v40
	v_and_b32_e32 v241, 0xffff0000, v40
	v_pk_mul_f32 v[240:241], v[240:241], v[240:241]
	v_and_b32_e32 v243, 0xffff0000, v42
	v_add_f32_e32 v244, v240, v241
	v_and_b32_e32 v242, 0xffff0000, v41
	v_add_f32_e32 v71, v71, v244
	v_lshlrev_b32_e32 v241, 16, v42
	v_lshlrev_b32_e32 v240, 16, v41
	v_pk_mul_f32 v[244:245], v[242:243], v[242:243]
	s_nop 0
	v_pk_fma_f32 v[244:245], v[240:241], v[240:241], v[244:245]
	s_nop 0
	v_add_f32_e32 v71, v71, v244
	v_add_f32_e32 v71, v71, v245
	v_lshlrev_b32_e32 v240, 16, v43
	v_and_b32_e32 v241, 0xffff0000, v43
	v_pk_mul_f32 v[240:241], v[240:241], v[240:241]
	s_nop 0
	v_add_f32_e32 v240, v240, v241
	v_add_f32_e32 v71, v71, v240
	s_waitcnt vmcnt(21)
	v_lshlrev_b32_e32 v240, 16, v44
	v_and_b32_e32 v241, 0xffff0000, v44
	v_pk_mul_f32 v[240:241], v[240:241], v[240:241]
	v_and_b32_e32 v243, 0xffff0000, v46
	v_add_f32_e32 v244, v240, v241
	v_and_b32_e32 v242, 0xffff0000, v45
	v_add_f32_e32 v71, v71, v244
	v_lshlrev_b32_e32 v241, 16, v46
	v_lshlrev_b32_e32 v240, 16, v45
	v_pk_mul_f32 v[244:245], v[242:243], v[242:243]
	s_nop 0
	v_pk_fma_f32 v[244:245], v[240:241], v[240:241], v[244:245]
	s_nop 0
	v_add_f32_e32 v71, v71, v244
	v_add_f32_e32 v71, v71, v245
	v_lshlrev_b32_e32 v240, 16, v47
	v_and_b32_e32 v241, 0xffff0000, v47
	v_pk_mul_f32 v[240:241], v[240:241], v[240:241]
	s_nop 0
	v_add_f32_e32 v240, v240, v241
	v_add_f32_e32 v71, v71, v240
	s_waitcnt vmcnt(20)
	v_lshlrev_b32_e32 v240, 16, v48
	v_and_b32_e32 v241, 0xffff0000, v48
	v_pk_mul_f32 v[240:241], v[240:241], v[240:241]
	v_and_b32_e32 v243, 0xffff0000, v50
	v_add_f32_e32 v244, v240, v241
	v_and_b32_e32 v242, 0xffff0000, v49
	v_add_f32_e32 v71, v71, v244
	v_lshlrev_b32_e32 v241, 16, v50
	v_lshlrev_b32_e32 v240, 16, v49
	v_pk_mul_f32 v[244:245], v[242:243], v[242:243]
	s_nop 0
	v_pk_fma_f32 v[244:245], v[240:241], v[240:241], v[244:245]
	s_nop 0
	v_add_f32_e32 v71, v71, v244
	v_add_f32_e32 v71, v71, v245
	v_lshlrev_b32_e32 v240, 16, v51
	v_and_b32_e32 v241, 0xffff0000, v51
	v_pk_mul_f32 v[240:241], v[240:241], v[240:241]
	s_nop 0
	v_add_f32_e32 v240, v240, v241
	v_add_f32_e32 v71, v71, v240
	s_waitcnt vmcnt(19)
	v_lshlrev_b32_e32 v240, 16, v52
	v_and_b32_e32 v241, 0xffff0000, v52
	v_pk_mul_f32 v[240:241], v[240:241], v[240:241]
	v_and_b32_e32 v243, 0xffff0000, v54
	v_add_f32_e32 v244, v240, v241
	v_and_b32_e32 v242, 0xffff0000, v53
	v_add_f32_e32 v71, v71, v244
	v_lshlrev_b32_e32 v241, 16, v54
	v_lshlrev_b32_e32 v240, 16, v53
	v_pk_mul_f32 v[244:245], v[242:243], v[242:243]
	s_nop 0
	v_pk_fma_f32 v[244:245], v[240:241], v[240:241], v[244:245]
	s_nop 0
	v_add_f32_e32 v71, v71, v244
	v_add_f32_e32 v71, v71, v245
	v_lshlrev_b32_e32 v240, 16, v55
	v_and_b32_e32 v241, 0xffff0000, v55
	v_pk_mul_f32 v[240:241], v[240:241], v[240:241]
	s_nop 0
	v_add_f32_e32 v240, v240, v241
	v_add_f32_e32 v71, v71, v240
	s_waitcnt vmcnt(18)
	v_lshlrev_b32_e32 v240, 16, v56
	v_and_b32_e32 v241, 0xffff0000, v56
	v_pk_mul_f32 v[240:241], v[240:241], v[240:241]
	v_and_b32_e32 v243, 0xffff0000, v58
	v_add_f32_e32 v244, v240, v241
	v_and_b32_e32 v242, 0xffff0000, v57
	v_add_f32_e32 v71, v71, v244
	v_lshlrev_b32_e32 v241, 16, v58
	v_lshlrev_b32_e32 v240, 16, v57
	v_pk_mul_f32 v[244:245], v[242:243], v[242:243]
	s_nop 0
	v_pk_fma_f32 v[244:245], v[240:241], v[240:241], v[244:245]
	s_nop 0
	v_add_f32_e32 v71, v71, v244
	v_add_f32_e32 v71, v71, v245
	v_lshlrev_b32_e32 v240, 16, v59
	v_and_b32_e32 v241, 0xffff0000, v59
	v_pk_mul_f32 v[240:241], v[240:241], v[240:241]
	s_nop 0
	v_add_f32_e32 v240, v240, v241
	v_add_f32_e32 v71, v71, v240
	s_waitcnt vmcnt(17)
	v_lshlrev_b32_e32 v240, 16, v60
	v_and_b32_e32 v241, 0xffff0000, v60
	v_pk_mul_f32 v[240:241], v[240:241], v[240:241]
	v_and_b32_e32 v243, 0xffff0000, v62
	v_add_f32_e32 v244, v240, v241
	v_and_b32_e32 v242, 0xffff0000, v61
	v_add_f32_e32 v71, v71, v244
	v_lshlrev_b32_e32 v241, 16, v62
	v_lshlrev_b32_e32 v240, 16, v61
	v_pk_mul_f32 v[244:245], v[242:243], v[242:243]
	s_nop 0
	v_pk_fma_f32 v[244:245], v[240:241], v[240:241], v[244:245]
	s_nop 0
	v_add_f32_e32 v71, v71, v244
	v_add_f32_e32 v71, v71, v245
	v_lshlrev_b32_e32 v240, 16, v63
	v_and_b32_e32 v241, 0xffff0000, v63
	v_pk_mul_f32 v[240:241], v[240:241], v[240:241]
	s_nop 0
	v_add_f32_e32 v240, v240, v241
	v_add_f32_e32 v71, v71, v240
	s_waitcnt vmcnt(16)
	v_lshlrev_b32_e32 v240, 16, v72
	v_and_b32_e32 v241, 0xffff0000, v72
	v_pk_mul_f32 v[240:241], v[240:241], v[240:241]
	v_and_b32_e32 v243, 0xffff0000, v74
	v_add_f32_e32 v244, v240, v241
	v_and_b32_e32 v242, 0xffff0000, v73
	v_add_f32_e32 v71, v71, v244
	v_lshlrev_b32_e32 v241, 16, v74
	v_lshlrev_b32_e32 v240, 16, v73
	v_pk_mul_f32 v[244:245], v[242:243], v[242:243]
	s_nop 0
	v_pk_fma_f32 v[244:245], v[240:241], v[240:241], v[244:245]
	s_nop 0
	v_add_f32_e32 v71, v71, v244
	v_add_f32_e32 v71, v71, v245
	v_lshlrev_b32_e32 v240, 16, v75
	v_and_b32_e32 v241, 0xffff0000, v75
	v_pk_mul_f32 v[240:241], v[240:241], v[240:241]
	s_nop 0
	v_add_f32_e32 v240, v240, v241
	v_add_f32_e32 v71, v71, v240
	s_waitcnt vmcnt(15)
	v_lshlrev_b32_e32 v240, 16, v76
	v_and_b32_e32 v241, 0xffff0000, v76
	v_pk_mul_f32 v[240:241], v[240:241], v[240:241]
	v_and_b32_e32 v243, 0xffff0000, v78
	v_add_f32_e32 v244, v240, v241
	v_and_b32_e32 v242, 0xffff0000, v77
	v_add_f32_e32 v71, v71, v244
	v_lshlrev_b32_e32 v241, 16, v78
	v_lshlrev_b32_e32 v240, 16, v77
	v_pk_mul_f32 v[244:245], v[242:243], v[242:243]
	s_nop 0
	v_pk_fma_f32 v[244:245], v[240:241], v[240:241], v[244:245]
	s_nop 0
	v_add_f32_e32 v71, v71, v244
	v_add_f32_e32 v71, v71, v245
	v_lshlrev_b32_e32 v240, 16, v79
	v_and_b32_e32 v241, 0xffff0000, v79
	v_pk_mul_f32 v[240:241], v[240:241], v[240:241]
	s_nop 0
	v_add_f32_e32 v240, v240, v241
	v_add_f32_e32 v71, v71, v240
	s_waitcnt vmcnt(14)
	v_lshlrev_b32_e32 v240, 16, v80
	v_and_b32_e32 v241, 0xffff0000, v80
	v_pk_mul_f32 v[240:241], v[240:241], v[240:241]
	v_and_b32_e32 v243, 0xffff0000, v82
	v_add_f32_e32 v244, v240, v241
	v_and_b32_e32 v242, 0xffff0000, v81
	v_add_f32_e32 v71, v71, v244
	v_lshlrev_b32_e32 v241, 16, v82
	v_lshlrev_b32_e32 v240, 16, v81
	v_pk_mul_f32 v[244:245], v[242:243], v[242:243]
	s_nop 0
	v_pk_fma_f32 v[244:245], v[240:241], v[240:241], v[244:245]
	s_nop 0
	v_add_f32_e32 v71, v71, v244
	v_add_f32_e32 v71, v71, v245
	v_lshlrev_b32_e32 v240, 16, v83
	v_and_b32_e32 v241, 0xffff0000, v83
	v_pk_mul_f32 v[240:241], v[240:241], v[240:241]
	s_nop 0
	v_add_f32_e32 v240, v240, v241
	v_add_f32_e32 v71, v71, v240
	s_waitcnt vmcnt(13)
	v_lshlrev_b32_e32 v240, 16, v84
	v_and_b32_e32 v241, 0xffff0000, v84
	v_pk_mul_f32 v[240:241], v[240:241], v[240:241]
	v_and_b32_e32 v243, 0xffff0000, v86
	v_add_f32_e32 v244, v240, v241
	v_and_b32_e32 v242, 0xffff0000, v85
	v_add_f32_e32 v71, v71, v244
	v_lshlrev_b32_e32 v241, 16, v86
	v_lshlrev_b32_e32 v240, 16, v85
	v_pk_mul_f32 v[244:245], v[242:243], v[242:243]
	s_nop 0
	v_pk_fma_f32 v[244:245], v[240:241], v[240:241], v[244:245]
	s_nop 0
	v_add_f32_e32 v71, v71, v244
	v_add_f32_e32 v71, v71, v245
	v_lshlrev_b32_e32 v240, 16, v87
	v_and_b32_e32 v241, 0xffff0000, v87
	v_pk_mul_f32 v[240:241], v[240:241], v[240:241]
	s_nop 0
	v_add_f32_e32 v240, v240, v241
	v_add_f32_e32 v71, v71, v240
	s_waitcnt vmcnt(12)
	v_lshlrev_b32_e32 v240, 16, v144
	v_and_b32_e32 v241, 0xffff0000, v144
	v_pk_mul_f32 v[240:241], v[240:241], v[240:241]
	v_and_b32_e32 v243, 0xffff0000, v146
	v_add_f32_e32 v244, v240, v241
	v_and_b32_e32 v242, 0xffff0000, v145
	v_add_f32_e32 v71, v71, v244
	v_lshlrev_b32_e32 v241, 16, v146
	v_lshlrev_b32_e32 v240, 16, v145
	v_pk_mul_f32 v[244:245], v[242:243], v[242:243]
	s_nop 0
	v_pk_fma_f32 v[244:245], v[240:241], v[240:241], v[244:245]
	s_nop 0
	v_add_f32_e32 v71, v71, v244
	v_add_f32_e32 v71, v71, v245
	v_lshlrev_b32_e32 v240, 16, v147
	v_and_b32_e32 v241, 0xffff0000, v147
	v_pk_mul_f32 v[240:241], v[240:241], v[240:241]
	s_nop 0
	v_add_f32_e32 v240, v240, v241
	v_add_f32_e32 v71, v71, v240
	s_waitcnt vmcnt(11)
	v_lshlrev_b32_e32 v240, 16, v148
	v_and_b32_e32 v241, 0xffff0000, v148
	v_pk_mul_f32 v[240:241], v[240:241], v[240:241]
	v_and_b32_e32 v243, 0xffff0000, v150
	v_add_f32_e32 v244, v240, v241
	v_and_b32_e32 v242, 0xffff0000, v149
	v_add_f32_e32 v71, v71, v244
	v_lshlrev_b32_e32 v241, 16, v150
	v_lshlrev_b32_e32 v240, 16, v149
	v_pk_mul_f32 v[244:245], v[242:243], v[242:243]
	s_nop 0
	v_pk_fma_f32 v[244:245], v[240:241], v[240:241], v[244:245]
	s_nop 0
	v_add_f32_e32 v71, v71, v244
	v_add_f32_e32 v71, v71, v245
	v_lshlrev_b32_e32 v240, 16, v151
	v_and_b32_e32 v241, 0xffff0000, v151
	v_pk_mul_f32 v[240:241], v[240:241], v[240:241]
	s_nop 0
	v_add_f32_e32 v240, v240, v241
	v_add_f32_e32 v71, v71, v240
	s_waitcnt vmcnt(10)
	v_lshlrev_b32_e32 v240, 16, v152
	v_and_b32_e32 v241, 0xffff0000, v152
	v_pk_mul_f32 v[240:241], v[240:241], v[240:241]
	v_and_b32_e32 v243, 0xffff0000, v154
	v_add_f32_e32 v244, v240, v241
	v_and_b32_e32 v242, 0xffff0000, v153
	v_add_f32_e32 v71, v71, v244
	v_lshlrev_b32_e32 v241, 16, v154
	v_lshlrev_b32_e32 v240, 16, v153
	v_pk_mul_f32 v[244:245], v[242:243], v[242:243]
	s_nop 0
	v_pk_fma_f32 v[244:245], v[240:241], v[240:241], v[244:245]
	s_nop 0
	v_add_f32_e32 v71, v71, v244
	v_add_f32_e32 v71, v71, v245
	v_lshlrev_b32_e32 v240, 16, v155
	v_and_b32_e32 v241, 0xffff0000, v155
	v_pk_mul_f32 v[240:241], v[240:241], v[240:241]
	s_nop 0
	v_add_f32_e32 v240, v240, v241
	v_add_f32_e32 v71, v71, v240
	s_waitcnt vmcnt(9)
	v_lshlrev_b32_e32 v240, 16, v156
	v_and_b32_e32 v241, 0xffff0000, v156
	v_pk_mul_f32 v[240:241], v[240:241], v[240:241]
	v_and_b32_e32 v243, 0xffff0000, v158
	v_add_f32_e32 v244, v240, v241
	v_and_b32_e32 v242, 0xffff0000, v157
	v_add_f32_e32 v71, v71, v244
	v_lshlrev_b32_e32 v241, 16, v158
	v_lshlrev_b32_e32 v240, 16, v157
	v_pk_mul_f32 v[244:245], v[242:243], v[242:243]
	s_nop 0
	v_pk_fma_f32 v[244:245], v[240:241], v[240:241], v[244:245]
	s_nop 0
	v_add_f32_e32 v71, v71, v244
	v_add_f32_e32 v71, v71, v245
	v_lshlrev_b32_e32 v240, 16, v159
	v_and_b32_e32 v241, 0xffff0000, v159
	v_pk_mul_f32 v[240:241], v[240:241], v[240:241]
	s_nop 0
	v_add_f32_e32 v240, v240, v241
	v_add_f32_e32 v71, v71, v240
	s_waitcnt vmcnt(8)
	v_lshlrev_b32_e32 v240, 16, v160
	v_and_b32_e32 v241, 0xffff0000, v160
	v_pk_mul_f32 v[240:241], v[240:241], v[240:241]
	v_and_b32_e32 v243, 0xffff0000, v162
	v_add_f32_e32 v244, v240, v241
	v_and_b32_e32 v242, 0xffff0000, v161
	v_add_f32_e32 v71, v71, v244
	v_lshlrev_b32_e32 v241, 16, v162
	v_lshlrev_b32_e32 v240, 16, v161
	v_pk_mul_f32 v[244:245], v[242:243], v[242:243]
	s_nop 0
	v_pk_fma_f32 v[244:245], v[240:241], v[240:241], v[244:245]
	s_nop 0
	v_add_f32_e32 v71, v71, v244
	v_add_f32_e32 v71, v71, v245
	v_lshlrev_b32_e32 v240, 16, v163
	v_and_b32_e32 v241, 0xffff0000, v163
	v_pk_mul_f32 v[240:241], v[240:241], v[240:241]
	s_nop 0
	v_add_f32_e32 v240, v240, v241
	v_add_f32_e32 v71, v71, v240
	s_waitcnt vmcnt(7)
	v_lshlrev_b32_e32 v240, 16, v164
	v_and_b32_e32 v241, 0xffff0000, v164
	v_pk_mul_f32 v[240:241], v[240:241], v[240:241]
	v_and_b32_e32 v243, 0xffff0000, v166
	v_add_f32_e32 v244, v240, v241
	v_and_b32_e32 v242, 0xffff0000, v165
	v_add_f32_e32 v71, v71, v244
	v_lshlrev_b32_e32 v241, 16, v166
	v_lshlrev_b32_e32 v240, 16, v165
	v_pk_mul_f32 v[244:245], v[242:243], v[242:243]
	s_nop 0
	v_pk_fma_f32 v[244:245], v[240:241], v[240:241], v[244:245]
	s_nop 0
	v_add_f32_e32 v71, v71, v244
	v_add_f32_e32 v71, v71, v245
	v_lshlrev_b32_e32 v240, 16, v167
	v_and_b32_e32 v241, 0xffff0000, v167
	v_pk_mul_f32 v[240:241], v[240:241], v[240:241]
	s_nop 0
	v_add_f32_e32 v240, v240, v241
	v_add_f32_e32 v71, v71, v240
	s_waitcnt vmcnt(6)
	v_lshlrev_b32_e32 v240, 16, v168
	v_and_b32_e32 v241, 0xffff0000, v168
	v_pk_mul_f32 v[240:241], v[240:241], v[240:241]
	v_and_b32_e32 v243, 0xffff0000, v170
	v_add_f32_e32 v244, v240, v241
	v_and_b32_e32 v242, 0xffff0000, v169
	v_add_f32_e32 v71, v71, v244
	v_lshlrev_b32_e32 v241, 16, v170
	v_lshlrev_b32_e32 v240, 16, v169
	v_pk_mul_f32 v[244:245], v[242:243], v[242:243]
	s_nop 0
	v_pk_fma_f32 v[244:245], v[240:241], v[240:241], v[244:245]
	s_nop 0
	v_add_f32_e32 v71, v71, v244
	v_add_f32_e32 v71, v71, v245
	v_lshlrev_b32_e32 v240, 16, v171
	v_and_b32_e32 v241, 0xffff0000, v171
	v_pk_mul_f32 v[240:241], v[240:241], v[240:241]
	s_nop 0
	v_add_f32_e32 v240, v240, v241
	v_add_f32_e32 v71, v71, v240
	s_waitcnt vmcnt(5)
	v_lshlrev_b32_e32 v240, 16, v172
	v_and_b32_e32 v241, 0xffff0000, v172
	v_pk_mul_f32 v[240:241], v[240:241], v[240:241]
	v_and_b32_e32 v243, 0xffff0000, v174
	v_add_f32_e32 v244, v240, v241
	v_and_b32_e32 v242, 0xffff0000, v173
	v_add_f32_e32 v71, v71, v244
	v_lshlrev_b32_e32 v241, 16, v174
	v_lshlrev_b32_e32 v240, 16, v173
	v_pk_mul_f32 v[244:245], v[242:243], v[242:243]
	s_nop 0
	v_pk_fma_f32 v[244:245], v[240:241], v[240:241], v[244:245]
	s_nop 0
	v_add_f32_e32 v71, v71, v244
	v_add_f32_e32 v71, v71, v245
	v_lshlrev_b32_e32 v240, 16, v175
	v_and_b32_e32 v241, 0xffff0000, v175
	v_pk_mul_f32 v[240:241], v[240:241], v[240:241]
	s_nop 0
	v_add_f32_e32 v240, v240, v241
	v_add_f32_e32 v71, v71, v240
	s_waitcnt vmcnt(4)
	v_lshlrev_b32_e32 v240, 16, v176
	v_and_b32_e32 v241, 0xffff0000, v176
	v_pk_mul_f32 v[240:241], v[240:241], v[240:241]
	v_and_b32_e32 v243, 0xffff0000, v178
	v_add_f32_e32 v244, v240, v241
	v_and_b32_e32 v242, 0xffff0000, v177
	v_add_f32_e32 v71, v71, v244
	v_lshlrev_b32_e32 v241, 16, v178
	v_lshlrev_b32_e32 v240, 16, v177
	v_pk_mul_f32 v[244:245], v[242:243], v[242:243]
	s_nop 0
	v_pk_fma_f32 v[244:245], v[240:241], v[240:241], v[244:245]
	s_nop 0
	v_add_f32_e32 v71, v71, v244
	v_add_f32_e32 v71, v71, v245
	v_lshlrev_b32_e32 v240, 16, v179
	v_and_b32_e32 v241, 0xffff0000, v179
	v_pk_mul_f32 v[240:241], v[240:241], v[240:241]
	s_nop 0
	v_add_f32_e32 v240, v240, v241
	v_add_f32_e32 v71, v71, v240
	s_waitcnt vmcnt(3)
	v_lshlrev_b32_e32 v240, 16, v180
	v_and_b32_e32 v241, 0xffff0000, v180
	v_pk_mul_f32 v[240:241], v[240:241], v[240:241]
	v_and_b32_e32 v243, 0xffff0000, v182
	v_add_f32_e32 v244, v240, v241
	v_and_b32_e32 v242, 0xffff0000, v181
	v_add_f32_e32 v71, v71, v244
	v_lshlrev_b32_e32 v241, 16, v182
	v_lshlrev_b32_e32 v240, 16, v181
	v_pk_mul_f32 v[244:245], v[242:243], v[242:243]
	s_nop 0
	v_pk_fma_f32 v[244:245], v[240:241], v[240:241], v[244:245]
	s_nop 0
	v_add_f32_e32 v71, v71, v244
	v_add_f32_e32 v71, v71, v245
	v_lshlrev_b32_e32 v240, 16, v183
	v_and_b32_e32 v241, 0xffff0000, v183
	v_pk_mul_f32 v[240:241], v[240:241], v[240:241]
	s_nop 0
	v_add_f32_e32 v240, v240, v241
	v_add_f32_e32 v71, v71, v240
	s_waitcnt vmcnt(2)
	v_lshlrev_b32_e32 v240, 16, v184
	v_and_b32_e32 v241, 0xffff0000, v184
	v_pk_mul_f32 v[240:241], v[240:241], v[240:241]
	v_and_b32_e32 v243, 0xffff0000, v186
	v_add_f32_e32 v244, v240, v241
	v_and_b32_e32 v242, 0xffff0000, v185
	v_add_f32_e32 v71, v71, v244
	v_lshlrev_b32_e32 v241, 16, v186
	v_lshlrev_b32_e32 v240, 16, v185
	v_pk_mul_f32 v[244:245], v[242:243], v[242:243]
	s_nop 0
	v_pk_fma_f32 v[244:245], v[240:241], v[240:241], v[244:245]
	s_nop 0
	v_add_f32_e32 v71, v71, v244
	v_add_f32_e32 v71, v71, v245
	v_lshlrev_b32_e32 v240, 16, v187
	v_and_b32_e32 v241, 0xffff0000, v187
	v_pk_mul_f32 v[240:241], v[240:241], v[240:241]
	s_nop 0
	v_add_f32_e32 v240, v240, v241
	v_add_f32_e32 v71, v71, v240
	s_waitcnt vmcnt(1)
	v_lshlrev_b32_e32 v240, 16, v188
	v_and_b32_e32 v241, 0xffff0000, v188
	v_pk_mul_f32 v[240:241], v[240:241], v[240:241]
	v_and_b32_e32 v243, 0xffff0000, v190
	v_add_f32_e32 v244, v240, v241
	v_and_b32_e32 v242, 0xffff0000, v189
	v_add_f32_e32 v71, v71, v244
	v_lshlrev_b32_e32 v241, 16, v190
	v_lshlrev_b32_e32 v240, 16, v189
	v_pk_mul_f32 v[244:245], v[242:243], v[242:243]
	s_nop 0
	v_pk_fma_f32 v[244:245], v[240:241], v[240:241], v[244:245]
	s_nop 0
	v_add_f32_e32 v71, v71, v244
	v_add_f32_e32 v71, v71, v245
	v_lshlrev_b32_e32 v240, 16, v191
	v_and_b32_e32 v241, 0xffff0000, v191
	v_pk_mul_f32 v[240:241], v[240:241], v[240:241]
	s_nop 0
	v_add_f32_e32 v240, v240, v241
	v_add_f32_e32 v71, v71, v240
	s_waitcnt vmcnt(0)
	v_lshlrev_b32_e32 v240, 16, v192
	v_and_b32_e32 v241, 0xffff0000, v192
	v_pk_mul_f32 v[240:241], v[240:241], v[240:241]
	v_and_b32_e32 v243, 0xffff0000, v194
	v_add_f32_e32 v244, v240, v241
	v_and_b32_e32 v242, 0xffff0000, v193
	v_add_f32_e32 v71, v71, v244
	v_lshlrev_b32_e32 v241, 16, v194
	v_lshlrev_b32_e32 v240, 16, v193
	v_pk_mul_f32 v[244:245], v[242:243], v[242:243]
	s_nop 0
	v_pk_fma_f32 v[244:245], v[240:241], v[240:241], v[244:245]
	s_nop 0
	v_add_f32_e32 v71, v71, v244
	v_add_f32_e32 v71, v71, v245
	v_lshlrev_b32_e32 v240, 16, v195
	v_and_b32_e32 v241, 0xffff0000, v195
	v_pk_mul_f32 v[240:241], v[240:241], v[240:241]
	s_nop 0
	v_add_f32_e32 v240, v240, v241
	v_add_f32_e32 v71, v71, v240
	s_nop 1
	v_add_f32_dpp v240, v71, v71 quad_perm:[1,0,3,2] row_mask:0xf bank_mask:0xf
	v_mul_f32_e32 v240, 0x3b000000, v240
	v_add_f32_e32 v240, 0x358637bd, v240
	v_rsq_f32_e32 v240, v240
	v_lshrrev_b32_e32 v241, 1, v196
	v_lshlrev_b32_e32 v241, 2, v241
	v_add_u32_e32 v241, 0x12000, v241
	v_and_b32_e32 v242, 1, v196
	v_cmp_eq_u32_e32 vcc, 0, v242
	s_nop 1
	s_and_saveexec_b64 s[0:1], vcc
	ds_write_b32 v241, v240
	s_or_b64 exec, exec, s[0:1]
	v_mov_b32_e32 v4, 0
	v_mov_b32_e32 v5, 0
	v_mov_b32_e32 v6, 0
	v_mov_b32_e32 v7, 0
	v_mov_b32_e32 v8, 0
	v_mov_b32_e32 v9, 0
	v_mov_b32_e32 v10, 0
	v_mov_b32_e32 v11, 0
	v_mov_b32_e32 v12, 0
	v_mov_b32_e32 v13, 0
	v_mov_b32_e32 v14, 0
	v_mov_b32_e32 v15, 0
	v_mov_b32_e32 v16, 0
	v_mov_b32_e32 v17, 0
	v_mov_b32_e32 v18, 0
	v_mov_b32_e32 v19, 0
	v_mov_b32_e32 v20, 0
	v_mov_b32_e32 v21, 0
	v_mov_b32_e32 v22, 0
	v_mov_b32_e32 v23, 0
	v_mov_b32_e32 v24, 0
	v_mov_b32_e32 v25, 0
	v_mov_b32_e32 v26, 0
	v_mov_b32_e32 v27, 0
	v_mov_b32_e32 v28, 0
	v_mov_b32_e32 v29, 0
	v_mov_b32_e32 v30, 0
	v_mov_b32_e32 v31, 0
	v_mov_b32_e32 v32, 0
	v_mov_b32_e32 v33, 0
	v_mov_b32_e32 v34, 0
	v_mov_b32_e32 v35, 0
	v_mov_b32_e32 v36, 0
	v_mov_b32_e32 v37, 0
	v_mov_b32_e32 v38, 0
	v_mov_b32_e32 v39, 0
	v_mov_b32_e32 v40, 0
	v_mov_b32_e32 v41, 0
	v_mov_b32_e32 v42, 0
	v_mov_b32_e32 v43, 0
	v_mov_b32_e32 v44, 0
	v_mov_b32_e32 v45, 0
	v_mov_b32_e32 v46, 0
	v_mov_b32_e32 v47, 0
	v_mov_b32_e32 v48, 0
	v_mov_b32_e32 v49, 0
	v_mov_b32_e32 v50, 0
	v_mov_b32_e32 v51, 0
	v_mov_b32_e32 v52, 0
	v_mov_b32_e32 v53, 0
	v_mov_b32_e32 v54, 0
	v_mov_b32_e32 v55, 0
	v_mov_b32_e32 v56, 0
	v_mov_b32_e32 v57, 0
	v_mov_b32_e32 v58, 0
	v_mov_b32_e32 v59, 0
	v_mov_b32_e32 v60, 0
	v_mov_b32_e32 v61, 0
	v_mov_b32_e32 v62, 0
	v_mov_b32_e32 v63, 0
	v_mov_b32_e32 v72, 0
	v_mov_b32_e32 v73, 0
	v_mov_b32_e32 v74, 0
	v_mov_b32_e32 v75, 0
	v_mov_b32_e32 v76, 0
	v_mov_b32_e32 v77, 0
	v_mov_b32_e32 v78, 0
	v_mov_b32_e32 v79, 0
	v_mov_b32_e32 v80, 0
	v_mov_b32_e32 v81, 0
	v_mov_b32_e32 v82, 0
	v_mov_b32_e32 v83, 0
	v_mov_b32_e32 v84, 0
	v_mov_b32_e32 v85, 0
	v_mov_b32_e32 v86, 0
	v_mov_b32_e32 v87, 0
	v_mov_b32_e32 v144, 0
	v_mov_b32_e32 v145, 0
	v_mov_b32_e32 v146, 0
	v_mov_b32_e32 v147, 0
	v_mov_b32_e32 v148, 0
	v_mov_b32_e32 v149, 0
	v_mov_b32_e32 v150, 0
	v_mov_b32_e32 v151, 0
	v_mov_b32_e32 v152, 0
	v_mov_b32_e32 v153, 0
	v_mov_b32_e32 v154, 0
	v_mov_b32_e32 v155, 0
	v_mov_b32_e32 v156, 0
	v_mov_b32_e32 v157, 0
	v_mov_b32_e32 v158, 0
	v_mov_b32_e32 v159, 0
	v_mov_b32_e32 v160, 0
	v_mov_b32_e32 v161, 0
	v_mov_b32_e32 v162, 0
	v_mov_b32_e32 v163, 0
	v_mov_b32_e32 v164, 0
	v_mov_b32_e32 v165, 0
	v_mov_b32_e32 v166, 0
	v_mov_b32_e32 v167, 0
	v_mov_b32_e32 v168, 0
	v_mov_b32_e32 v169, 0
	v_mov_b32_e32 v170, 0
	v_mov_b32_e32 v171, 0
	v_mov_b32_e32 v172, 0
	v_mov_b32_e32 v173, 0
	v_mov_b32_e32 v174, 0
	v_mov_b32_e32 v175, 0
	v_mov_b32_e32 v176, 0
	v_mov_b32_e32 v177, 0
	v_mov_b32_e32 v178, 0
	v_mov_b32_e32 v179, 0
	v_mov_b32_e32 v180, 0
	v_mov_b32_e32 v181, 0
	v_mov_b32_e32 v182, 0
	v_mov_b32_e32 v183, 0
	v_mov_b32_e32 v184, 0
	v_mov_b32_e32 v185, 0
	v_mov_b32_e32 v186, 0
	v_mov_b32_e32 v187, 0
	v_mov_b32_e32 v188, 0
	v_mov_b32_e32 v189, 0
	v_mov_b32_e32 v190, 0
	v_mov_b32_e32 v191, 0
	v_mov_b32_e32 v192, 0
	v_mov_b32_e32 v193, 0
	v_mov_b32_e32 v194, 0
	v_mov_b32_e32 v195, 0
	s_mov_b32 s17, 0
	s_mov_b32 s36, 0
	s_mov_b32 s37, 0xc000
.Luq_loop:
	s_waitcnt vmcnt(6)
	s_barrier
	s_cmp_lt_u32 s17, 14
	s_cbranch_scc0 .Luq_nofill
	s_add_i32 s0, s16, s37
	s_mov_b32 m0, s0
	s_nop 0
	global_load_lds_dwordx4 v2, s[10:11]
	s_add_i32 m0, s0, 0x1000
	s_nop 0
	global_load_lds_dwordx4 v3, s[10:11]
	s_add_i32 m0, s0, 0x2000
	s_nop 0
	global_load_lds_dwordx4 v2, s[12:13]
	s_add_i32 m0, s0, 0x3000
	s_nop 0
	global_load_lds_dwordx4 v3, s[12:13]
	s_add_i32 m0, s0, 0x4000
	s_nop 0
	global_load_lds_dwordx4 v2, s[14:15]
	s_add_i32 m0, s0, 0x5000
	s_nop 0
	global_load_lds_dwordx4 v3, s[14:15]
	v_add_u32_e32 v2, 64, v2
	v_add_u32_e32 v3, 64, v3
.Luq_nofill:
	v_add_u32_e32 v220, s36, v64
	v_add_u32_e32 v227, s36, v65
	ds_read_b128 v[216:219], v220
	ds_read_b128 v[228:231], v220 offset:1024
	ds_read_b128 v[232:235], v220 offset:2048
	ds_read_b128 v[236:239], v220 offset:3072
	ds_read_b128 v[240:243], v227 offset:8192
	ds_read_b128 v[244:247], v227 offset:9216
	ds_read_b128 v[248:251], v227 offset:10240
	ds_read_b128 v[252:255], v227 offset:11264
	s_waitcnt lgkmcnt(3)
	v_mfma_f32_16x16x32_bf16 v[4:7], v[240:243], v[216:219], v[4:7]
	v_mfma_f32_16x16x32_bf16 v[20:23], v[240:243], v[228:231], v[20:23]
	v_mfma_f32_16x16x32_bf16 v[36:39], v[240:243], v[232:235], v[36:39]
	v_mfma_f32_16x16x32_bf16 v[52:55], v[240:243], v[236:239], v[52:55]
	ds_read_b128 v[240:243], v227 offset:16384
	s_waitcnt lgkmcnt(3)
	v_mfma_f32_16x16x32_bf16 v[8:11], v[244:247], v[216:219], v[8:11]
	v_mfma_f32_16x16x32_bf16 v[24:27], v[244:247], v[228:231], v[24:27]
	v_mfma_f32_16x16x32_bf16 v[40:43], v[244:247], v[232:235], v[40:43]
	v_mfma_f32_16x16x32_bf16 v[56:59], v[244:247], v[236:239], v[56:59]
	ds_read_b128 v[244:247], v227 offset:17408
	s_waitcnt lgkmcnt(3)
	v_mfma_f32_16x16x32_bf16 v[12:15], v[248:251], v[216:219], v[12:15]
	v_mfma_f32_16x16x32_bf16 v[28:31], v[248:251], v[228:231], v[28:31]
	v_mfma_f32_16x16x32_bf16 v[44:47], v[248:251], v[232:235], v[44:47]
	v_mfma_f32_16x16x32_bf16 v[60:63], v[248:251], v[236:239], v[60:63]
	ds_read_b128 v[248:251], v227 offset:18432
	s_waitcnt lgkmcnt(3)
	v_mfma_f32_16x16x32_bf16 v[16:19], v[252:255], v[216:219], v[16:19]
	v_mfma_f32_16x16x32_bf16 v[32:35], v[252:255], v[228:231], v[32:35]
	v_mfma_f32_16x16x32_bf16 v[48:51], v[252:255], v[232:235], v[48:51]
	v_mfma_f32_16x16x32_bf16 v[72:75], v[252:255], v[236:239], v[72:75]
	ds_read_b128 v[252:255], v227 offset:19456
	s_waitcnt lgkmcnt(3)
	v_mfma_f32_16x16x32_bf16 v[76:79], v[240:243], v[216:219], v[76:79]
	v_mfma_f32_16x16x32_bf16 v[148:151], v[240:243], v[228:231], v[148:151]
	v_mfma_f32_16x16x32_bf16 v[164:167], v[240:243], v[232:235], v[164:167]
	v_mfma_f32_16x16x32_bf16 v[180:183], v[240:243], v[236:239], v[180:183]
	s_waitcnt lgkmcnt(2)
	v_mfma_f32_16x16x32_bf16 v[80:83], v[244:247], v[216:219], v[80:83]
	v_mfma_f32_16x16x32_bf16 v[152:155], v[244:247], v[228:231], v[152:155]
	v_mfma_f32_16x16x32_bf16 v[168:171], v[244:247], v[232:235], v[168:171]
	v_mfma_f32_16x16x32_bf16 v[184:187], v[244:247], v[236:239], v[184:187]
	s_waitcnt lgkmcnt(1)
	v_mfma_f32_16x16x32_bf16 v[84:87], v[248:251], v[216:219], v[84:87]
	v_mfma_f32_16x16x32_bf16 v[156:159], v[248:251], v[228:231], v[156:159]
	v_mfma_f32_16x16x32_bf16 v[172:175], v[248:251], v[232:235], v[172:175]
	v_mfma_f32_16x16x32_bf16 v[188:191], v[248:251], v[236:239], v[188:191]
	s_waitcnt lgkmcnt(0)
	v_mfma_f32_16x16x32_bf16 v[144:147], v[252:255], v[216:219], v[144:147]
	v_mfma_f32_16x16x32_bf16 v[160:163], v[252:255], v[228:231], v[160:163]
	v_mfma_f32_16x16x32_bf16 v[176:179], v[252:255], v[232:235], v[176:179]
	v_mfma_f32_16x16x32_bf16 v[192:195], v[252:255], v[236:239], v[192:195]
	s_add_i32 s36, s36, 0x6000
	s_cmp_eq_u32 s36, 0x12000
	s_cselect_b32 s36, 0, s36
	s_add_i32 s37, s37, 0x6000
	s_cmp_eq_u32 s37, 0x12000
	s_cselect_b32 s37, 0, s37
	s_add_i32 s17, s17, 1
	s_cmp_lt_u32 s17, 15
	s_cbranch_scc1 .Luq_loop
	s_waitcnt vmcnt(0)
	s_barrier
	v_add_u32_e32 v220, s36, v64
	v_add_u32_e32 v227, s36, v65
	ds_read_b128 v[216:219], v220
	ds_read_b128 v[228:231], v220 offset:1024
	ds_read_b128 v[232:235], v220 offset:2048
	ds_read_b128 v[236:239], v220 offset:3072
	ds_read_b128 v[240:243], v227 offset:8192
	ds_read_b128 v[244:247], v227 offset:9216
	ds_read_b128 v[248:251], v227 offset:10240
	ds_read_b128 v[252:255], v227 offset:11264
	s_waitcnt lgkmcnt(3)
	v_mfma_f32_16x16x32_bf16 v[4:7], v[240:243], v[216:219], v[4:7]
	v_mfma_f32_16x16x32_bf16 v[20:23], v[240:243], v[228:231], v[20:23]
	v_mfma_f32_16x16x32_bf16 v[36:39], v[240:243], v[232:235], v[36:39]
	v_mfma_f32_16x16x32_bf16 v[52:55], v[240:243], v[236:239], v[52:55]
	ds_read_b128 v[240:243], v227 offset:16384
	s_waitcnt lgkmcnt(3)
	v_mfma_f32_16x16x32_bf16 v[8:11], v[244:247], v[216:219], v[8:11]
	v_mfma_f32_16x16x32_bf16 v[24:27], v[244:247], v[228:231], v[24:27]
	v_mfma_f32_16x16x32_bf16 v[40:43], v[244:247], v[232:235], v[40:43]
	v_mfma_f32_16x16x32_bf16 v[56:59], v[244:247], v[236:239], v[56:59]
	ds_read_b128 v[244:247], v227 offset:17408
	s_waitcnt lgkmcnt(3)
	v_mfma_f32_16x16x32_bf16 v[12:15], v[248:251], v[216:219], v[12:15]
	v_mfma_f32_16x16x32_bf16 v[28:31], v[248:251], v[228:231], v[28:31]
	v_mfma_f32_16x16x32_bf16 v[44:47], v[248:251], v[232:235], v[44:47]
	v_mfma_f32_16x16x32_bf16 v[60:63], v[248:251], v[236:239], v[60:63]
	ds_read_b128 v[248:251], v227 offset:18432
	s_waitcnt lgkmcnt(3)
	v_mfma_f32_16x16x32_bf16 v[16:19], v[252:255], v[216:219], v[16:19]
	v_mfma_f32_16x16x32_bf16 v[32:35], v[252:255], v[228:231], v[32:35]
	v_mfma_f32_16x16x32_bf16 v[48:51], v[252:255], v[232:235], v[48:51]
	v_mfma_f32_16x16x32_bf16 v[72:75], v[252:255], v[236:239], v[72:75]
	ds_read_b128 v[252:255], v227 offset:19456
	s_waitcnt lgkmcnt(3)
	v_mfma_f32_16x16x32_bf16 v[76:79], v[240:243], v[216:219], v[76:79]
	v_mfma_f32_16x16x32_bf16 v[148:151], v[240:243], v[228:231], v[148:151]
	v_mfma_f32_16x16x32_bf16 v[164:167], v[240:243], v[232:235], v[164:167]
	v_mfma_f32_16x16x32_bf16 v[180:183], v[240:243], v[236:239], v[180:183]
	s_waitcnt lgkmcnt(2)
	v_mfma_f32_16x16x32_bf16 v[80:83], v[244:247], v[216:219], v[80:83]
	v_mfma_f32_16x16x32_bf16 v[152:155], v[244:247], v[228:231], v[152:155]
	v_mfma_f32_16x16x32_bf16 v[168:171], v[244:247], v[232:235], v[168:171]
	v_mfma_f32_16x16x32_bf16 v[184:187], v[244:247], v[236:239], v[184:187]
	s_waitcnt lgkmcnt(1)
	v_mfma_f32_16x16x32_bf16 v[84:87], v[248:251], v[216:219], v[84:87]
	v_mfma_f32_16x16x32_bf16 v[156:159], v[248:251], v[228:231], v[156:159]
	v_mfma_f32_16x16x32_bf16 v[172:175], v[248:251], v[232:235], v[172:175]
	v_mfma_f32_16x16x32_bf16 v[188:191], v[248:251], v[236:239], v[188:191]
	s_waitcnt lgkmcnt(0)
	v_mfma_f32_16x16x32_bf16 v[144:147], v[252:255], v[216:219], v[144:147]
	v_mfma_f32_16x16x32_bf16 v[160:163], v[252:255], v[228:231], v[160:163]
	v_mfma_f32_16x16x32_bf16 v[176:179], v[252:255], v[232:235], v[176:179]
	v_mfma_f32_16x16x32_bf16 v[192:195], v[252:255], v[236:239], v[192:195]
	s_barrier
	v_and_b32_e32 v213, 15, v196
	v_lshrrev_b32_e32 v220, 7, v196
	v_cvt_f32_u32_e32 v228, v213
	v_add_f32_e32 v229, 0x41800000, v228
	v_add_f32_e32 v230, 0x42000000, v228
	v_add_f32_e32 v231, 0x42400000, v228
	v_add_u32_e32 v0, s26, v220
	v_cvt_f32_u32_e32 v236, v0
	v_and_b32_e32 v0, 16, v196
	v_cmp_ne_u32_e32 vcc, 0, v0
	v_mov_b32_e32 v232, 1.0
	v_mov_b32_e32 v0, 0x3c23d70a
	v_cndmask_b32_e32 v232, v232, v0, vcc
	v_mov_b32_e32 v233, 0x3ea1e89b
	v_mov_b32_e32 v0, 0x3b4f3e37
	v_cndmask_b32_e32 v233, v233, v0, vcc
	v_mov_b32_e32 v234, 0x3dcccccd
	v_mov_b32_e32 v0, 0x3a83126f
	v_cndmask_b32_e32 v234, v234, v0, vcc
	v_mov_b32_e32 v235, 0x3d0186e2
	v_mov_b32_e32 v0, 0x39a5cb5f
	v_cndmask_b32_e32 v235, v235, v0, vcc
	s_mov_b32 s50, -1
	s_mov_b32 s51, 0
	v_lshl_add_u32 v213, v220, 6, v213
	v_lshl_add_u32 v227, v213, 2, 0
	v_add_u32_e32 v227, 0x12000, v227
	v_mul_u32_u24_e32 v213, 0x110, v213
	v_bfe_u32 v220, v196, 6, 1
	s_nop 1
	v_readfirstlane_b32 s1, v220
	v_lshl_add_u32 v213, v220, 7, v213
	v_bfe_u32 v220, v196, 4, 2
	v_lshl_add_u32 v213, v220, 3, v213
	v_lshrrev_b32_e32 v220, 4, v196
	v_and_b32_e32 v0, 15, v196
	v_lshlrev_b32_e32 v0, 4, v0
	v_mad_u32_u24 v143, v220, s30, v0
	s_movk_i32 s0, 0x600
	v_mad_u32_u24 v71, v220, s0, v0
	s_lshl_b32 s1, s1, 2
	s_lshl_b32 s0, s19, 4
	s_add_i32 s19, s0, s1
	ds_read_b32 v216, v227 offset:0
	ds_read_b32 v217, v227 offset:64
	ds_read_b32 v218, v227 offset:128
	ds_read_b32 v219, v227 offset:192
	s_waitcnt lgkmcnt(0)
	v_mul_f32_e32 v216, 0x3e16c740, v216
	v_mul_f32_e32 v217, 0x3e16c740, v217
	v_mul_f32_e32 v218, 0x3e16c740, v218
	v_mul_f32_e32 v219, 0x3e16c740, v219
	s_add_u32 s46, s48, 0x1031c000
	s_addc_u32 s47, s49, 0
	s_add_u32 s46, s46, s18
	s_addc_u32 s47, s47, 0
	v_mul_f32_e32 v4, v4, v216
	v_mul_f32_e32 v5, v5, v216
	v_mul_f32_e32 v6, v6, v216
	v_mul_f32_e32 v7, v7, v216
	v_mul_f32_e32 v20, v20, v217
	v_mul_f32_e32 v21, v21, v217
	v_mul_f32_e32 v22, v22, v217
	v_mul_f32_e32 v23, v23, v217
	v_mul_f32_e32 v36, v36, v218
	v_mul_f32_e32 v37, v37, v218
	v_mul_f32_e32 v38, v38, v218
	v_mul_f32_e32 v39, v39, v218
	v_mul_f32_e32 v52, v52, v219
	v_mul_f32_e32 v53, v53, v219
	v_mul_f32_e32 v54, v54, v219
	v_mul_f32_e32 v55, v55, v219
	s_add_i32 s0, s19, 0
	s_mul_hi_u32 s1, s0, 0x2aaaaaab
	s_mul_i32 s1, s1, 6
	s_sub_i32 s0, s0, s1
	s_cmp_lt_u32 s0, 4
	s_cbranch_scc1 .Luq_nr0_0
	s_cmp_lg_u32 s27, 0
	s_cbranch_scc1 .Luq_nr0_0
	s_cmp_eq_u32 s0, 5
	s_cbranch_scc1 .Luq_h10_0
	v_mov_b32_e32 v240, v236
	v_mov_b32_e32 v241, v236
	v_mov_b32_e32 v242, v236
	v_mov_b32_e32 v243, v236
	s_branch .Luq_rp0_0
.Luq_h10_0:
	v_mov_b32_e32 v240, v228
	v_mov_b32_e32 v241, v229
	v_mov_b32_e32 v242, v230
	v_mov_b32_e32 v243, v231
.Luq_rp0_0:
	v_mul_f32_e32 v244, v232, v240
	v_mul_f32_e32 v245, v233, v240
	v_mul_f32_e32 v244, 0.15915494, v244
	v_mul_f32_e32 v245, 0.15915494, v245
	v_mov_b32_e32 v250, v4
	v_mov_b32_e32 v251, v5
	v_mov_b32_e32 v252, v4
	v_mov_b32_e32 v253, v5
	v_sin_f32_e32 v246, v244
	v_sin_f32_e32 v247, v245
	v_cos_f32_e32 v248, v244
	v_cos_f32_e32 v249, v245
	v_permlane32_swap_b32_e32 v250, v252
	v_permlane32_swap_b32_e32 v251, v253
	v_cndmask_b32_e64 v244, v248, -v246, s[50:51]
	v_cndmask_b32_e64 v245, v249, -v247, s[50:51]
	v_cndmask_b32_e64 v246, v246, v248, s[50:51]
	v_cndmask_b32_e64 v247, v247, v249, s[50:51]
	v_mul_f32_e32 v254, v252, v244
	v_mul_f32_e32 v255, v253, v245
	v_fma_f32 v4, v250, v246, v254
	v_fma_f32 v5, v251, v247, v255
	v_mul_f32_e32 v244, v234, v240
	v_mul_f32_e32 v245, v235, v240
	v_mul_f32_e32 v244, 0.15915494, v244
	v_mul_f32_e32 v245, 0.15915494, v245
	v_mov_b32_e32 v250, v6
	v_mov_b32_e32 v251, v7
	v_mov_b32_e32 v252, v6
	v_mov_b32_e32 v253, v7
	v_sin_f32_e32 v246, v244
	v_sin_f32_e32 v247, v245
	v_cos_f32_e32 v248, v244
	v_cos_f32_e32 v249, v245
	v_permlane32_swap_b32_e32 v250, v252
	v_permlane32_swap_b32_e32 v251, v253
	v_cndmask_b32_e64 v244, v248, -v246, s[50:51]
	v_cndmask_b32_e64 v245, v249, -v247, s[50:51]
	v_cndmask_b32_e64 v246, v246, v248, s[50:51]
	v_cndmask_b32_e64 v247, v247, v249, s[50:51]
	v_mul_f32_e32 v254, v252, v244
	v_mul_f32_e32 v255, v253, v245
	v_fma_f32 v6, v250, v246, v254
	v_fma_f32 v7, v251, v247, v255
	v_mul_f32_e32 v244, v232, v241
	v_mul_f32_e32 v245, v233, v241
	v_mul_f32_e32 v244, 0.15915494, v244
	v_mul_f32_e32 v245, 0.15915494, v245
	v_mov_b32_e32 v250, v20
	v_mov_b32_e32 v251, v21
	v_mov_b32_e32 v252, v20
	v_mov_b32_e32 v253, v21
	v_sin_f32_e32 v246, v244
	v_sin_f32_e32 v247, v245
	v_cos_f32_e32 v248, v244
	v_cos_f32_e32 v249, v245
	v_permlane32_swap_b32_e32 v250, v252
	v_permlane32_swap_b32_e32 v251, v253
	v_cndmask_b32_e64 v244, v248, -v246, s[50:51]
	v_cndmask_b32_e64 v245, v249, -v247, s[50:51]
	v_cndmask_b32_e64 v246, v246, v248, s[50:51]
	v_cndmask_b32_e64 v247, v247, v249, s[50:51]
	v_mul_f32_e32 v254, v252, v244
	v_mul_f32_e32 v255, v253, v245
	v_fma_f32 v20, v250, v246, v254
	v_fma_f32 v21, v251, v247, v255
	v_mul_f32_e32 v244, v234, v241
	v_mul_f32_e32 v245, v235, v241
	v_mul_f32_e32 v244, 0.15915494, v244
	v_mul_f32_e32 v245, 0.15915494, v245
	v_mov_b32_e32 v250, v22
	v_mov_b32_e32 v251, v23
	v_mov_b32_e32 v252, v22
	v_mov_b32_e32 v253, v23
	v_sin_f32_e32 v246, v244
	v_sin_f32_e32 v247, v245
	v_cos_f32_e32 v248, v244
	v_cos_f32_e32 v249, v245
	v_permlane32_swap_b32_e32 v250, v252
	v_permlane32_swap_b32_e32 v251, v253
	v_cndmask_b32_e64 v244, v248, -v246, s[50:51]
	v_cndmask_b32_e64 v245, v249, -v247, s[50:51]
	v_cndmask_b32_e64 v246, v246, v248, s[50:51]
	v_cndmask_b32_e64 v247, v247, v249, s[50:51]
	v_mul_f32_e32 v254, v252, v244
	v_mul_f32_e32 v255, v253, v245
	v_fma_f32 v22, v250, v246, v254
	v_fma_f32 v23, v251, v247, v255
	v_mul_f32_e32 v244, v232, v242
	v_mul_f32_e32 v245, v233, v242
	v_mul_f32_e32 v244, 0.15915494, v244
	v_mul_f32_e32 v245, 0.15915494, v245
	v_mov_b32_e32 v250, v36
	v_mov_b32_e32 v251, v37
	v_mov_b32_e32 v252, v36
	v_mov_b32_e32 v253, v37
	v_sin_f32_e32 v246, v244
	v_sin_f32_e32 v247, v245
	v_cos_f32_e32 v248, v244
	v_cos_f32_e32 v249, v245
	v_permlane32_swap_b32_e32 v250, v252
	v_permlane32_swap_b32_e32 v251, v253
	v_cndmask_b32_e64 v244, v248, -v246, s[50:51]
	v_cndmask_b32_e64 v245, v249, -v247, s[50:51]
	v_cndmask_b32_e64 v246, v246, v248, s[50:51]
	v_cndmask_b32_e64 v247, v247, v249, s[50:51]
	v_mul_f32_e32 v254, v252, v244
	v_mul_f32_e32 v255, v253, v245
	v_fma_f32 v36, v250, v246, v254
	v_fma_f32 v37, v251, v247, v255
	v_mul_f32_e32 v244, v234, v242
	v_mul_f32_e32 v245, v235, v242
	v_mul_f32_e32 v244, 0.15915494, v244
	v_mul_f32_e32 v245, 0.15915494, v245
	v_mov_b32_e32 v250, v38
	v_mov_b32_e32 v251, v39
	v_mov_b32_e32 v252, v38
	v_mov_b32_e32 v253, v39
	v_sin_f32_e32 v246, v244
	v_sin_f32_e32 v247, v245
	v_cos_f32_e32 v248, v244
	v_cos_f32_e32 v249, v245
	v_permlane32_swap_b32_e32 v250, v252
	v_permlane32_swap_b32_e32 v251, v253
	v_cndmask_b32_e64 v244, v248, -v246, s[50:51]
	v_cndmask_b32_e64 v245, v249, -v247, s[50:51]
	v_cndmask_b32_e64 v246, v246, v248, s[50:51]
	v_cndmask_b32_e64 v247, v247, v249, s[50:51]
	v_mul_f32_e32 v254, v252, v244
	v_mul_f32_e32 v255, v253, v245
	v_fma_f32 v38, v250, v246, v254
	v_fma_f32 v39, v251, v247, v255
	v_mul_f32_e32 v244, v232, v243
	v_mul_f32_e32 v245, v233, v243
	v_mul_f32_e32 v244, 0.15915494, v244
	v_mul_f32_e32 v245, 0.15915494, v245
	v_mov_b32_e32 v250, v52
	v_mov_b32_e32 v251, v53
	v_mov_b32_e32 v252, v52
	v_mov_b32_e32 v253, v53
	v_sin_f32_e32 v246, v244
	v_sin_f32_e32 v247, v245
	v_cos_f32_e32 v248, v244
	v_cos_f32_e32 v249, v245
	v_permlane32_swap_b32_e32 v250, v252
	v_permlane32_swap_b32_e32 v251, v253
	v_cndmask_b32_e64 v244, v248, -v246, s[50:51]
	v_cndmask_b32_e64 v245, v249, -v247, s[50:51]
	v_cndmask_b32_e64 v246, v246, v248, s[50:51]
	v_cndmask_b32_e64 v247, v247, v249, s[50:51]
	v_mul_f32_e32 v254, v252, v244
	v_mul_f32_e32 v255, v253, v245
	v_fma_f32 v52, v250, v246, v254
	v_fma_f32 v53, v251, v247, v255
	v_mul_f32_e32 v244, v234, v243
	v_mul_f32_e32 v245, v235, v243
	v_mul_f32_e32 v244, 0.15915494, v244
	v_mul_f32_e32 v245, 0.15915494, v245
	v_mov_b32_e32 v250, v54
	v_mov_b32_e32 v251, v55
	v_mov_b32_e32 v252, v54
	v_mov_b32_e32 v253, v55
	v_sin_f32_e32 v246, v244
	v_sin_f32_e32 v247, v245
	v_cos_f32_e32 v248, v244
	v_cos_f32_e32 v249, v245
	v_permlane32_swap_b32_e32 v250, v252
	v_permlane32_swap_b32_e32 v251, v253
	v_cndmask_b32_e64 v244, v248, -v246, s[50:51]
	v_cndmask_b32_e64 v245, v249, -v247, s[50:51]
	v_cndmask_b32_e64 v246, v246, v248, s[50:51]
	v_cndmask_b32_e64 v247, v247, v249, s[50:51]
	v_mul_f32_e32 v254, v252, v244
	v_mul_f32_e32 v255, v253, v245
	v_fma_f32 v54, v250, v246, v254
	v_fma_f32 v55, v251, v247, v255
.Luq_nr0_0:
	v_cvt_pk_bf16_f32 v2, v4, v5
	v_cvt_pk_bf16_f32 v3, v6, v7
	ds_write_b64 v213, v[2:3] offset:0
	v_cvt_pk_bf16_f32 v214, v20, v21
	v_cvt_pk_bf16_f32 v215, v22, v23
	ds_write_b64 v213, v[214:215] offset:4352
	v_cvt_pk_bf16_f32 v2, v36, v37
	v_cvt_pk_bf16_f32 v3, v38, v39
	ds_write_b64 v213, v[2:3] offset:8704
	v_cvt_pk_bf16_f32 v214, v52, v53
	v_cvt_pk_bf16_f32 v215, v54, v55
	ds_write_b64 v213, v[214:215] offset:13056
	v_mul_f32_e32 v8, v8, v216
	v_mul_f32_e32 v9, v9, v216
	v_mul_f32_e32 v10, v10, v216
	v_mul_f32_e32 v11, v11, v216
	v_mul_f32_e32 v24, v24, v217
	v_mul_f32_e32 v25, v25, v217
	v_mul_f32_e32 v26, v26, v217
	v_mul_f32_e32 v27, v27, v217
	v_mul_f32_e32 v40, v40, v218
	v_mul_f32_e32 v41, v41, v218
	v_mul_f32_e32 v42, v42, v218
	v_mul_f32_e32 v43, v43, v218
	v_mul_f32_e32 v56, v56, v219
	v_mul_f32_e32 v57, v57, v219
	v_mul_f32_e32 v58, v58, v219
	v_mul_f32_e32 v59, v59, v219
	s_add_i32 s0, s19, 1
	s_mul_hi_u32 s1, s0, 0x2aaaaaab
	s_mul_i32 s1, s1, 6
	s_sub_i32 s0, s0, s1
	s_cmp_lt_u32 s0, 4
	s_cbranch_scc1 .Luq_nr0_1
	s_cmp_lg_u32 s27, 0
	s_cbranch_scc1 .Luq_nr0_1
	s_cmp_eq_u32 s0, 5
	s_cbranch_scc1 .Luq_h10_1
	v_mov_b32_e32 v240, v236
	v_mov_b32_e32 v241, v236
	v_mov_b32_e32 v242, v236
	v_mov_b32_e32 v243, v236
	s_branch .Luq_rp0_1

.Luq_rp0_1:
	v_mul_f32_e32 v244, v232, v240
	v_mul_f32_e32 v245, v233, v240
	v_mul_f32_e32 v244, 0.15915494, v244
	v_mul_f32_e32 v245, 0.15915494, v245
	v_mov_b32_e32 v250, v8
	v_mov_b32_e32 v251, v9
	v_mov_b32_e32 v252, v8
	v_mov_b32_e32 v253, v9
	v_sin_f32_e32 v246, v244
	v_sin_f32_e32 v247, v245
	v_cos_f32_e32 v248, v244
	v_cos_f32_e32 v249, v245
	v_permlane32_swap_b32_e32 v250, v252
	v_permlane32_swap_b32_e32 v251, v253
	v_cndmask_b32_e64 v244, v248, -v246, s[50:51]
	v_cndmask_b32_e64 v245, v249, -v247, s[50:51]
	v_cndmask_b32_e64 v246, v246, v248, s[50:51]
	v_cndmask_b32_e64 v247, v247, v249, s[50:51]
	v_mul_f32_e32 v254, v252, v244
	v_mul_f32_e32 v255, v253, v245
	v_fma_f32 v8, v250, v246, v254
	v_fma_f32 v9, v251, v247, v255
	v_mul_f32_e32 v244, v234, v240
	v_mul_f32_e32 v245, v235, v240
	v_mul_f32_e32 v244, 0.15915494, v244
	v_mul_f32_e32 v245, 0.15915494, v245
	v_mov_b32_e32 v250, v10
	v_mov_b32_e32 v251, v11
	v_mov_b32_e32 v252, v10
	v_mov_b32_e32 v253, v11
	v_sin_f32_e32 v246, v244
	v_sin_f32_e32 v247, v245
	v_cos_f32_e32 v248, v244
	v_cos_f32_e32 v249, v245
	v_permlane32_swap_b32_e32 v250, v252
	v_permlane32_swap_b32_e32 v251, v253
	v_cndmask_b32_e64 v244, v248, -v246, s[50:51]
	v_cndmask_b32_e64 v245, v249, -v247, s[50:51]
	v_cndmask_b32_e64 v246, v246, v248, s[50:51]
	v_cndmask_b32_e64 v247, v247, v249, s[50:51]
	v_mul_f32_e32 v254, v252, v244
	v_mul_f32_e32 v255, v253, v245
	v_fma_f32 v10, v250, v246, v254
	v_fma_f32 v11, v251, v247, v255
	v_mul_f32_e32 v244, v232, v241
	v_mul_f32_e32 v245, v233, v241
	v_mul_f32_e32 v244, 0.15915494, v244
	v_mul_f32_e32 v245, 0.15915494, v245
	v_mov_b32_e32 v250, v24
	v_mov_b32_e32 v251, v25
	v_mov_b32_e32 v252, v24
	v_mov_b32_e32 v253, v25
	v_sin_f32_e32 v246, v244
	v_sin_f32_e32 v247, v245
	v_cos_f32_e32 v248, v244
	v_cos_f32_e32 v249, v245
	v_permlane32_swap_b32_e32 v250, v252
	v_permlane32_swap_b32_e32 v251, v253
	v_cndmask_b32_e64 v244, v248, -v246, s[50:51]
	v_cndmask_b32_e64 v245, v249, -v247, s[50:51]
	v_cndmask_b32_e64 v246, v246, v248, s[50:51]
	v_cndmask_b32_e64 v247, v247, v249, s[50:51]
	v_mul_f32_e32 v254, v252, v244
	v_mul_f32_e32 v255, v253, v245
	v_fma_f32 v24, v250, v246, v254
	v_fma_f32 v25, v251, v247, v255
	v_mul_f32_e32 v244, v234, v241
	v_mul_f32_e32 v245, v235, v241
	v_mul_f32_e32 v244, 0.15915494, v244
	v_mul_f32_e32 v245, 0.15915494, v245
	v_mov_b32_e32 v250, v26
	v_mov_b32_e32 v251, v27
	v_mov_b32_e32 v252, v26
	v_mov_b32_e32 v253, v27
	v_sin_f32_e32 v246, v244
	v_sin_f32_e32 v247, v245
	v_cos_f32_e32 v248, v244
	v_cos_f32_e32 v249, v245
	v_permlane32_swap_b32_e32 v250, v252
	v_permlane32_swap_b32_e32 v251, v253
	v_cndmask_b32_e64 v244, v248, -v246, s[50:51]
	v_cndmask_b32_e64 v245, v249, -v247, s[50:51]
	v_cndmask_b32_e64 v246, v246, v248, s[50:51]
	v_cndmask_b32_e64 v247, v247, v249, s[50:51]
	v_mul_f32_e32 v254, v252, v244
	v_mul_f32_e32 v255, v253, v245
	v_fma_f32 v26, v250, v246, v254
	v_fma_f32 v27, v251, v247, v255
	v_mul_f32_e32 v244, v232, v242
	v_mul_f32_e32 v245, v233, v242
	v_mul_f32_e32 v244, 0.15915494, v244
	v_mul_f32_e32 v245, 0.15915494, v245
	v_mov_b32_e32 v250, v40
	v_mov_b32_e32 v251, v41
	v_mov_b32_e32 v252, v40
	v_mov_b32_e32 v253, v41
	v_sin_f32_e32 v246, v244
	v_sin_f32_e32 v247, v245
	v_cos_f32_e32 v248, v244
	v_cos_f32_e32 v249, v245
	v_permlane32_swap_b32_e32 v250, v252
	v_permlane32_swap_b32_e32 v251, v253
	v_cndmask_b32_e64 v244, v248, -v246, s[50:51]
	v_cndmask_b32_e64 v245, v249, -v247, s[50:51]
	v_cndmask_b32_e64 v246, v246, v248, s[50:51]
	v_cndmask_b32_e64 v247, v247, v249, s[50:51]
	v_mul_f32_e32 v254, v252, v244
	v_mul_f32_e32 v255, v253, v245
	v_fma_f32 v40, v250, v246, v254
	v_fma_f32 v41, v251, v247, v255
	v_mul_f32_e32 v244, v234, v242
	v_mul_f32_e32 v245, v235, v242
	v_mul_f32_e32 v244, 0.15915494, v244
	v_mul_f32_e32 v245, 0.15915494, v245
	v_mov_b32_e32 v250, v42
	v_mov_b32_e32 v251, v43
	v_mov_b32_e32 v252, v42
	v_mov_b32_e32 v253, v43
	v_sin_f32_e32 v246, v244
	v_sin_f32_e32 v247, v245
	v_cos_f32_e32 v248, v244
	v_cos_f32_e32 v249, v245
	v_permlane32_swap_b32_e32 v250, v252
	v_permlane32_swap_b32_e32 v251, v253
	v_cndmask_b32_e64 v244, v248, -v246, s[50:51]
	v_cndmask_b32_e64 v245, v249, -v247, s[50:51]
	v_cndmask_b32_e64 v246, v246, v248, s[50:51]
	v_cndmask_b32_e64 v247, v247, v249, s[50:51]
	v_mul_f32_e32 v254, v252, v244
	v_mul_f32_e32 v255, v253, v245
	v_fma_f32 v42, v250, v246, v254
	v_fma_f32 v43, v251, v247, v255
	v_mul_f32_e32 v244, v232, v243
	v_mul_f32_e32 v245, v233, v243
	v_mul_f32_e32 v244, 0.15915494, v244
	v_mul_f32_e32 v245, 0.15915494, v245
	v_mov_b32_e32 v250, v56
	v_mov_b32_e32 v251, v57
	v_mov_b32_e32 v252, v56
	v_mov_b32_e32 v253, v57
	v_sin_f32_e32 v246, v244
	v_sin_f32_e32 v247, v245
	v_cos_f32_e32 v248, v244
	v_cos_f32_e32 v249, v245
	v_permlane32_swap_b32_e32 v250, v252
	v_permlane32_swap_b32_e32 v251, v253
	v_cndmask_b32_e64 v244, v248, -v246, s[50:51]
	v_cndmask_b32_e64 v245, v249, -v247, s[50:51]
	v_cndmask_b32_e64 v246, v246, v248, s[50:51]
	v_cndmask_b32_e64 v247, v247, v249, s[50:51]
	v_mul_f32_e32 v254, v252, v244
	v_mul_f32_e32 v255, v253, v245
	v_fma_f32 v56, v250, v246, v254
	v_fma_f32 v57, v251, v247, v255
	v_mul_f32_e32 v244, v234, v243
	v_mul_f32_e32 v245, v235, v243
	v_mul_f32_e32 v244, 0.15915494, v244
	v_mul_f32_e32 v245, 0.15915494, v245
	v_mov_b32_e32 v250, v58
	v_mov_b32_e32 v251, v59
	v_mov_b32_e32 v252, v58
	v_mov_b32_e32 v253, v59
	v_sin_f32_e32 v246, v244
	v_sin_f32_e32 v247, v245
	v_cos_f32_e32 v248, v244
	v_cos_f32_e32 v249, v245
	v_permlane32_swap_b32_e32 v250, v252
	v_permlane32_swap_b32_e32 v251, v253
	v_cndmask_b32_e64 v244, v248, -v246, s[50:51]
	v_cndmask_b32_e64 v245, v249, -v247, s[50:51]
	v_cndmask_b32_e64 v246, v246, v248, s[50:51]
	v_cndmask_b32_e64 v247, v247, v249, s[50:51]
	v_mul_f32_e32 v254, v252, v244
	v_mul_f32_e32 v255, v253, v245
	v_fma_f32 v58, v250, v246, v254
	v_fma_f32 v59, v251, v247, v255
.Luq_nr0_1:
	v_cvt_pk_bf16_f32 v2, v8, v9
	v_cvt_pk_bf16_f32 v3, v10, v11
	ds_write_b64 v213, v[2:3] offset:32
	v_cvt_pk_bf16_f32 v214, v24, v25
	v_cvt_pk_bf16_f32 v215, v26, v27
	ds_write_b64 v213, v[214:215] offset:4384
	v_cvt_pk_bf16_f32 v2, v40, v41
	v_cvt_pk_bf16_f32 v3, v42, v43
	ds_write_b64 v213, v[2:3] offset:8736
	v_cvt_pk_bf16_f32 v214, v56, v57
	v_cvt_pk_bf16_f32 v215, v58, v59
	ds_write_b64 v213, v[214:215] offset:13088
	v_mul_f32_e32 v12, v12, v216
	v_mul_f32_e32 v13, v13, v216
	v_mul_f32_e32 v14, v14, v216
	v_mul_f32_e32 v15, v15, v216
	v_mul_f32_e32 v28, v28, v217
	v_mul_f32_e32 v29, v29, v217
	v_mul_f32_e32 v30, v30, v217
	v_mul_f32_e32 v31, v31, v217
	v_mul_f32_e32 v44, v44, v218
	v_mul_f32_e32 v45, v45, v218
	v_mul_f32_e32 v46, v46, v218
	v_mul_f32_e32 v47, v47, v218
	v_mul_f32_e32 v60, v60, v219
	v_mul_f32_e32 v61, v61, v219
	v_mul_f32_e32 v62, v62, v219
	v_mul_f32_e32 v63, v63, v219
	s_add_i32 s0, s19, 2
	s_mul_hi_u32 s1, s0, 0x2aaaaaab
	s_mul_i32 s1, s1, 6
	s_sub_i32 s0, s0, s1
	s_cmp_lt_u32 s0, 4
	s_cbranch_scc1 .Luq_nr0_2
	s_cmp_lg_u32 s27, 0
	s_cbranch_scc1 .Luq_nr0_2
	s_cmp_eq_u32 s0, 5
	s_cbranch_scc1 .Luq_h10_2
	v_mov_b32_e32 v240, v236
	v_mov_b32_e32 v241, v236
	v_mov_b32_e32 v242, v236
	v_mov_b32_e32 v243, v236
	s_branch .Luq_rp0_2

.Luq_rp0_2:
	v_mul_f32_e32 v244, v232, v240
	v_mul_f32_e32 v245, v233, v240
	v_mul_f32_e32 v244, 0.15915494, v244
	v_mul_f32_e32 v245, 0.15915494, v245
	v_mov_b32_e32 v250, v12
	v_mov_b32_e32 v251, v13
	v_mov_b32_e32 v252, v12
	v_mov_b32_e32 v253, v13
	v_sin_f32_e32 v246, v244
	v_sin_f32_e32 v247, v245
	v_cos_f32_e32 v248, v244
	v_cos_f32_e32 v249, v245
	v_permlane32_swap_b32_e32 v250, v252
	v_permlane32_swap_b32_e32 v251, v253
	v_cndmask_b32_e64 v244, v248, -v246, s[50:51]
	v_cndmask_b32_e64 v245, v249, -v247, s[50:51]
	v_cndmask_b32_e64 v246, v246, v248, s[50:51]
	v_cndmask_b32_e64 v247, v247, v249, s[50:51]
	v_mul_f32_e32 v254, v252, v244
	v_mul_f32_e32 v255, v253, v245
	v_fma_f32 v12, v250, v246, v254
	v_fma_f32 v13, v251, v247, v255
	v_mul_f32_e32 v244, v234, v240
	v_mul_f32_e32 v245, v235, v240
	v_mul_f32_e32 v244, 0.15915494, v244
	v_mul_f32_e32 v245, 0.15915494, v245
	v_mov_b32_e32 v250, v14
	v_mov_b32_e32 v251, v15
	v_mov_b32_e32 v252, v14
	v_mov_b32_e32 v253, v15
	v_sin_f32_e32 v246, v244
	v_sin_f32_e32 v247, v245
	v_cos_f32_e32 v248, v244
	v_cos_f32_e32 v249, v245
	v_permlane32_swap_b32_e32 v250, v252
	v_permlane32_swap_b32_e32 v251, v253
	v_cndmask_b32_e64 v244, v248, -v246, s[50:51]
	v_cndmask_b32_e64 v245, v249, -v247, s[50:51]
	v_cndmask_b32_e64 v246, v246, v248, s[50:51]
	v_cndmask_b32_e64 v247, v247, v249, s[50:51]
	v_mul_f32_e32 v254, v252, v244
	v_mul_f32_e32 v255, v253, v245
	v_fma_f32 v14, v250, v246, v254
	v_fma_f32 v15, v251, v247, v255
	v_mul_f32_e32 v244, v232, v241
	v_mul_f32_e32 v245, v233, v241
	v_mul_f32_e32 v244, 0.15915494, v244
	v_mul_f32_e32 v245, 0.15915494, v245
	v_mov_b32_e32 v250, v28
	v_mov_b32_e32 v251, v29
	v_mov_b32_e32 v252, v28
	v_mov_b32_e32 v253, v29
	v_sin_f32_e32 v246, v244
	v_sin_f32_e32 v247, v245
	v_cos_f32_e32 v248, v244
	v_cos_f32_e32 v249, v245
	v_permlane32_swap_b32_e32 v250, v252
	v_permlane32_swap_b32_e32 v251, v253
	v_cndmask_b32_e64 v244, v248, -v246, s[50:51]
	v_cndmask_b32_e64 v245, v249, -v247, s[50:51]
	v_cndmask_b32_e64 v246, v246, v248, s[50:51]
	v_cndmask_b32_e64 v247, v247, v249, s[50:51]
	v_mul_f32_e32 v254, v252, v244
	v_mul_f32_e32 v255, v253, v245
	v_fma_f32 v28, v250, v246, v254
	v_fma_f32 v29, v251, v247, v255
	v_mul_f32_e32 v244, v234, v241
	v_mul_f32_e32 v245, v235, v241
	v_mul_f32_e32 v244, 0.15915494, v244
	v_mul_f32_e32 v245, 0.15915494, v245
	v_mov_b32_e32 v250, v30
	v_mov_b32_e32 v251, v31
	v_mov_b32_e32 v252, v30
	v_mov_b32_e32 v253, v31
	v_sin_f32_e32 v246, v244
	v_sin_f32_e32 v247, v245
	v_cos_f32_e32 v248, v244
	v_cos_f32_e32 v249, v245
	v_permlane32_swap_b32_e32 v250, v252
	v_permlane32_swap_b32_e32 v251, v253
	v_cndmask_b32_e64 v244, v248, -v246, s[50:51]
	v_cndmask_b32_e64 v245, v249, -v247, s[50:51]
	v_cndmask_b32_e64 v246, v246, v248, s[50:51]
	v_cndmask_b32_e64 v247, v247, v249, s[50:51]
	v_mul_f32_e32 v254, v252, v244
	v_mul_f32_e32 v255, v253, v245
	v_fma_f32 v30, v250, v246, v254
	v_fma_f32 v31, v251, v247, v255
	v_mul_f32_e32 v244, v232, v242
	v_mul_f32_e32 v245, v233, v242
	v_mul_f32_e32 v244, 0.15915494, v244
	v_mul_f32_e32 v245, 0.15915494, v245
	v_mov_b32_e32 v250, v44
	v_mov_b32_e32 v251, v45
	v_mov_b32_e32 v252, v44
	v_mov_b32_e32 v253, v45
	v_sin_f32_e32 v246, v244
	v_sin_f32_e32 v247, v245
	v_cos_f32_e32 v248, v244
	v_cos_f32_e32 v249, v245
	v_permlane32_swap_b32_e32 v250, v252
	v_permlane32_swap_b32_e32 v251, v253
	v_cndmask_b32_e64 v244, v248, -v246, s[50:51]
	v_cndmask_b32_e64 v245, v249, -v247, s[50:51]
	v_cndmask_b32_e64 v246, v246, v248, s[50:51]
	v_cndmask_b32_e64 v247, v247, v249, s[50:51]
	v_mul_f32_e32 v254, v252, v244
	v_mul_f32_e32 v255, v253, v245
	v_fma_f32 v44, v250, v246, v254
	v_fma_f32 v45, v251, v247, v255
	v_mul_f32_e32 v244, v234, v242
	v_mul_f32_e32 v245, v235, v242
	v_mul_f32_e32 v244, 0.15915494, v244
	v_mul_f32_e32 v245, 0.15915494, v245
	v_mov_b32_e32 v250, v46
	v_mov_b32_e32 v251, v47
	v_mov_b32_e32 v252, v46
	v_mov_b32_e32 v253, v47
	v_sin_f32_e32 v246, v244
	v_sin_f32_e32 v247, v245
	v_cos_f32_e32 v248, v244
	v_cos_f32_e32 v249, v245
	v_permlane32_swap_b32_e32 v250, v252
	v_permlane32_swap_b32_e32 v251, v253
	v_cndmask_b32_e64 v244, v248, -v246, s[50:51]
	v_cndmask_b32_e64 v245, v249, -v247, s[50:51]
	v_cndmask_b32_e64 v246, v246, v248, s[50:51]
	v_cndmask_b32_e64 v247, v247, v249, s[50:51]
	v_mul_f32_e32 v254, v252, v244
	v_mul_f32_e32 v255, v253, v245
	v_fma_f32 v46, v250, v246, v254
	v_fma_f32 v47, v251, v247, v255
	v_mul_f32_e32 v244, v232, v243
	v_mul_f32_e32 v245, v233, v243
	v_mul_f32_e32 v244, 0.15915494, v244
	v_mul_f32_e32 v245, 0.15915494, v245
	v_mov_b32_e32 v250, v60
	v_mov_b32_e32 v251, v61
	v_mov_b32_e32 v252, v60
	v_mov_b32_e32 v253, v61
	v_sin_f32_e32 v246, v244
	v_sin_f32_e32 v247, v245
	v_cos_f32_e32 v248, v244
	v_cos_f32_e32 v249, v245
	v_permlane32_swap_b32_e32 v250, v252
	v_permlane32_swap_b32_e32 v251, v253
	v_cndmask_b32_e64 v244, v248, -v246, s[50:51]
	v_cndmask_b32_e64 v245, v249, -v247, s[50:51]
	v_cndmask_b32_e64 v246, v246, v248, s[50:51]
	v_cndmask_b32_e64 v247, v247, v249, s[50:51]
	v_mul_f32_e32 v254, v252, v244
	v_mul_f32_e32 v255, v253, v245
	v_fma_f32 v60, v250, v246, v254
	v_fma_f32 v61, v251, v247, v255
	v_mul_f32_e32 v244, v234, v243
	v_mul_f32_e32 v245, v235, v243
	v_mul_f32_e32 v244, 0.15915494, v244
	v_mul_f32_e32 v245, 0.15915494, v245
	v_mov_b32_e32 v250, v62
	v_mov_b32_e32 v251, v63
	v_mov_b32_e32 v252, v62
	v_mov_b32_e32 v253, v63
	v_sin_f32_e32 v246, v244
	v_sin_f32_e32 v247, v245
	v_cos_f32_e32 v248, v244
	v_cos_f32_e32 v249, v245
	v_permlane32_swap_b32_e32 v250, v252
	v_permlane32_swap_b32_e32 v251, v253
	v_cndmask_b32_e64 v244, v248, -v246, s[50:51]
	v_cndmask_b32_e64 v245, v249, -v247, s[50:51]
	v_cndmask_b32_e64 v246, v246, v248, s[50:51]
	v_cndmask_b32_e64 v247, v247, v249, s[50:51]
	v_mul_f32_e32 v254, v252, v244
	v_mul_f32_e32 v255, v253, v245
	v_fma_f32 v62, v250, v246, v254
	v_fma_f32 v63, v251, v247, v255
.Luq_nr0_2:
	v_cvt_pk_bf16_f32 v2, v12, v13
	v_cvt_pk_bf16_f32 v3, v14, v15
	ds_write_b64 v213, v[2:3] offset:64
	v_cvt_pk_bf16_f32 v214, v28, v29
	v_cvt_pk_bf16_f32 v215, v30, v31
	ds_write_b64 v213, v[214:215] offset:4416
	v_cvt_pk_bf16_f32 v2, v44, v45
	v_cvt_pk_bf16_f32 v3, v46, v47
	ds_write_b64 v213, v[2:3] offset:8768
	v_cvt_pk_bf16_f32 v214, v60, v61
	v_cvt_pk_bf16_f32 v215, v62, v63
	ds_write_b64 v213, v[214:215] offset:13120
	v_mul_f32_e32 v16, v16, v216
	v_mul_f32_e32 v17, v17, v216
	v_mul_f32_e32 v18, v18, v216
	v_mul_f32_e32 v19, v19, v216
	v_mul_f32_e32 v32, v32, v217
	v_mul_f32_e32 v33, v33, v217
	v_mul_f32_e32 v34, v34, v217
	v_mul_f32_e32 v35, v35, v217
	v_mul_f32_e32 v48, v48, v218
	v_mul_f32_e32 v49, v49, v218
	v_mul_f32_e32 v50, v50, v218
	v_mul_f32_e32 v51, v51, v218
	v_mul_f32_e32 v72, v72, v219
	v_mul_f32_e32 v73, v73, v219
	v_mul_f32_e32 v74, v74, v219
	v_mul_f32_e32 v75, v75, v219
	s_add_i32 s0, s19, 3
	s_mul_hi_u32 s1, s0, 0x2aaaaaab
	s_mul_i32 s1, s1, 6
	s_sub_i32 s0, s0, s1
	s_cmp_lt_u32 s0, 4
	s_cbranch_scc1 .Luq_nr0_3
	s_cmp_lg_u32 s27, 0
	s_cbranch_scc1 .Luq_nr0_3
	s_cmp_eq_u32 s0, 5
	s_cbranch_scc1 .Luq_h10_3
	v_mov_b32_e32 v240, v236
	v_mov_b32_e32 v241, v236
	v_mov_b32_e32 v242, v236
	v_mov_b32_e32 v243, v236
	s_branch .Luq_rp0_3

.Luq_rp0_3:
	v_mul_f32_e32 v244, v232, v240
	v_mul_f32_e32 v245, v233, v240
	v_mul_f32_e32 v244, 0.15915494, v244
	v_mul_f32_e32 v245, 0.15915494, v245
	v_mov_b32_e32 v250, v16
	v_mov_b32_e32 v251, v17
	v_mov_b32_e32 v252, v16
	v_mov_b32_e32 v253, v17
	v_sin_f32_e32 v246, v244
	v_sin_f32_e32 v247, v245
	v_cos_f32_e32 v248, v244
	v_cos_f32_e32 v249, v245
	v_permlane32_swap_b32_e32 v250, v252
	v_permlane32_swap_b32_e32 v251, v253
	v_cndmask_b32_e64 v244, v248, -v246, s[50:51]
	v_cndmask_b32_e64 v245, v249, -v247, s[50:51]
	v_cndmask_b32_e64 v246, v246, v248, s[50:51]
	v_cndmask_b32_e64 v247, v247, v249, s[50:51]
	v_mul_f32_e32 v254, v252, v244
	v_mul_f32_e32 v255, v253, v245
	v_fma_f32 v16, v250, v246, v254
	v_fma_f32 v17, v251, v247, v255
	v_mul_f32_e32 v244, v234, v240
	v_mul_f32_e32 v245, v235, v240
	v_mul_f32_e32 v244, 0.15915494, v244
	v_mul_f32_e32 v245, 0.15915494, v245
	v_mov_b32_e32 v250, v18
	v_mov_b32_e32 v251, v19
	v_mov_b32_e32 v252, v18
	v_mov_b32_e32 v253, v19
	v_sin_f32_e32 v246, v244
	v_sin_f32_e32 v247, v245
	v_cos_f32_e32 v248, v244
	v_cos_f32_e32 v249, v245
	v_permlane32_swap_b32_e32 v250, v252
	v_permlane32_swap_b32_e32 v251, v253
	v_cndmask_b32_e64 v244, v248, -v246, s[50:51]
	v_cndmask_b32_e64 v245, v249, -v247, s[50:51]
	v_cndmask_b32_e64 v246, v246, v248, s[50:51]
	v_cndmask_b32_e64 v247, v247, v249, s[50:51]
	v_mul_f32_e32 v254, v252, v244
	v_mul_f32_e32 v255, v253, v245
	v_fma_f32 v18, v250, v246, v254
	v_fma_f32 v19, v251, v247, v255
	v_mul_f32_e32 v244, v232, v241
	v_mul_f32_e32 v245, v233, v241
	v_mul_f32_e32 v244, 0.15915494, v244
	v_mul_f32_e32 v245, 0.15915494, v245
	v_mov_b32_e32 v250, v32
	v_mov_b32_e32 v251, v33
	v_mov_b32_e32 v252, v32
	v_mov_b32_e32 v253, v33
	v_sin_f32_e32 v246, v244
	v_sin_f32_e32 v247, v245
	v_cos_f32_e32 v248, v244
	v_cos_f32_e32 v249, v245
	v_permlane32_swap_b32_e32 v250, v252
	v_permlane32_swap_b32_e32 v251, v253
	v_cndmask_b32_e64 v244, v248, -v246, s[50:51]
	v_cndmask_b32_e64 v245, v249, -v247, s[50:51]
	v_cndmask_b32_e64 v246, v246, v248, s[50:51]
	v_cndmask_b32_e64 v247, v247, v249, s[50:51]
	v_mul_f32_e32 v254, v252, v244
	v_mul_f32_e32 v255, v253, v245
	v_fma_f32 v32, v250, v246, v254
	v_fma_f32 v33, v251, v247, v255
	v_mul_f32_e32 v244, v234, v241
	v_mul_f32_e32 v245, v235, v241
	v_mul_f32_e32 v244, 0.15915494, v244
	v_mul_f32_e32 v245, 0.15915494, v245
	v_mov_b32_e32 v250, v34
	v_mov_b32_e32 v251, v35
	v_mov_b32_e32 v252, v34
	v_mov_b32_e32 v253, v35
	v_sin_f32_e32 v246, v244
	v_sin_f32_e32 v247, v245
	v_cos_f32_e32 v248, v244
	v_cos_f32_e32 v249, v245
	v_permlane32_swap_b32_e32 v250, v252
	v_permlane32_swap_b32_e32 v251, v253
	v_cndmask_b32_e64 v244, v248, -v246, s[50:51]
	v_cndmask_b32_e64 v245, v249, -v247, s[50:51]
	v_cndmask_b32_e64 v246, v246, v248, s[50:51]
	v_cndmask_b32_e64 v247, v247, v249, s[50:51]
	v_mul_f32_e32 v254, v252, v244
	v_mul_f32_e32 v255, v253, v245
	v_fma_f32 v34, v250, v246, v254
	v_fma_f32 v35, v251, v247, v255
	v_mul_f32_e32 v244, v232, v242
	v_mul_f32_e32 v245, v233, v242
	v_mul_f32_e32 v244, 0.15915494, v244
	v_mul_f32_e32 v245, 0.15915494, v245
	v_mov_b32_e32 v250, v48
	v_mov_b32_e32 v251, v49
	v_mov_b32_e32 v252, v48
	v_mov_b32_e32 v253, v49
	v_sin_f32_e32 v246, v244
	v_sin_f32_e32 v247, v245
	v_cos_f32_e32 v248, v244
	v_cos_f32_e32 v249, v245
	v_permlane32_swap_b32_e32 v250, v252
	v_permlane32_swap_b32_e32 v251, v253
	v_cndmask_b32_e64 v244, v248, -v246, s[50:51]
	v_cndmask_b32_e64 v245, v249, -v247, s[50:51]
	v_cndmask_b32_e64 v246, v246, v248, s[50:51]
	v_cndmask_b32_e64 v247, v247, v249, s[50:51]
	v_mul_f32_e32 v254, v252, v244
	v_mul_f32_e32 v255, v253, v245
	v_fma_f32 v48, v250, v246, v254
	v_fma_f32 v49, v251, v247, v255
	v_mul_f32_e32 v244, v234, v242
	v_mul_f32_e32 v245, v235, v242
	v_mul_f32_e32 v244, 0.15915494, v244
	v_mul_f32_e32 v245, 0.15915494, v245
	v_mov_b32_e32 v250, v50
	v_mov_b32_e32 v251, v51
	v_mov_b32_e32 v252, v50
	v_mov_b32_e32 v253, v51
	v_sin_f32_e32 v246, v244
	v_sin_f32_e32 v247, v245
	v_cos_f32_e32 v248, v244
	v_cos_f32_e32 v249, v245
	v_permlane32_swap_b32_e32 v250, v252
	v_permlane32_swap_b32_e32 v251, v253
	v_cndmask_b32_e64 v244, v248, -v246, s[50:51]
	v_cndmask_b32_e64 v245, v249, -v247, s[50:51]
	v_cndmask_b32_e64 v246, v246, v248, s[50:51]
	v_cndmask_b32_e64 v247, v247, v249, s[50:51]
	v_mul_f32_e32 v254, v252, v244
	v_mul_f32_e32 v255, v253, v245
	v_fma_f32 v50, v250, v246, v254
	v_fma_f32 v51, v251, v247, v255
	v_mul_f32_e32 v244, v232, v243
	v_mul_f32_e32 v245, v233, v243
	v_mul_f32_e32 v244, 0.15915494, v244
	v_mul_f32_e32 v245, 0.15915494, v245
	v_mov_b32_e32 v250, v72
	v_mov_b32_e32 v251, v73
	v_mov_b32_e32 v252, v72
	v_mov_b32_e32 v253, v73
	v_sin_f32_e32 v246, v244
	v_sin_f32_e32 v247, v245
	v_cos_f32_e32 v248, v244
	v_cos_f32_e32 v249, v245
	v_permlane32_swap_b32_e32 v250, v252
	v_permlane32_swap_b32_e32 v251, v253
	v_cndmask_b32_e64 v244, v248, -v246, s[50:51]
	v_cndmask_b32_e64 v245, v249, -v247, s[50:51]
	v_cndmask_b32_e64 v246, v246, v248, s[50:51]
	v_cndmask_b32_e64 v247, v247, v249, s[50:51]
	v_mul_f32_e32 v254, v252, v244
	v_mul_f32_e32 v255, v253, v245
	v_fma_f32 v72, v250, v246, v254
	v_fma_f32 v73, v251, v247, v255
	v_mul_f32_e32 v244, v234, v243
	v_mul_f32_e32 v245, v235, v243
	v_mul_f32_e32 v244, 0.15915494, v244
	v_mul_f32_e32 v245, 0.15915494, v245
	v_mov_b32_e32 v250, v74
	v_mov_b32_e32 v251, v75
	v_mov_b32_e32 v252, v74
	v_mov_b32_e32 v253, v75
	v_sin_f32_e32 v246, v244
	v_sin_f32_e32 v247, v245
	v_cos_f32_e32 v248, v244
	v_cos_f32_e32 v249, v245
	v_permlane32_swap_b32_e32 v250, v252
	v_permlane32_swap_b32_e32 v251, v253
	v_cndmask_b32_e64 v244, v248, -v246, s[50:51]
	v_cndmask_b32_e64 v245, v249, -v247, s[50:51]
	v_cndmask_b32_e64 v246, v246, v248, s[50:51]
	v_cndmask_b32_e64 v247, v247, v249, s[50:51]
	v_mul_f32_e32 v254, v252, v244
	v_mul_f32_e32 v255, v253, v245
	v_fma_f32 v74, v250, v246, v254
	v_fma_f32 v75, v251, v247, v255
.Luq_nr0_3:
	v_cvt_pk_bf16_f32 v2, v16, v17
	v_cvt_pk_bf16_f32 v3, v18, v19
	ds_write_b64 v213, v[2:3] offset:96
	v_cvt_pk_bf16_f32 v214, v32, v33
	v_cvt_pk_bf16_f32 v215, v34, v35
	ds_write_b64 v213, v[214:215] offset:4448
	v_cvt_pk_bf16_f32 v2, v48, v49
	v_cvt_pk_bf16_f32 v3, v50, v51
	ds_write_b64 v213, v[2:3] offset:8800
	v_cvt_pk_bf16_f32 v214, v72, v73
	v_cvt_pk_bf16_f32 v215, v74, v75
	ds_write_b64 v213, v[214:215] offset:13152
	s_waitcnt lgkmcnt(0)
	s_barrier
	ds_read_b128 v[4:7], v143 offset:0
	ds_read_b128 v[8:11], v143 offset:4352
	ds_read_b128 v[12:15], v143 offset:8704
	ds_read_b128 v[16:19], v143 offset:13056
	ds_read_b128 v[20:23], v143 offset:17408
	ds_read_b128 v[24:27], v143 offset:21760
	ds_read_b128 v[28:31], v143 offset:26112
	ds_read_b128 v[32:35], v143 offset:30464
	v_mov_b32_e32 v220, v71
	s_waitcnt lgkmcnt(7)
	global_store_dwordx4 v220, v[4:7], s[46:47]
	v_add_u32_e32 v220, 0x6000, v220
	s_waitcnt lgkmcnt(6)
	global_store_dwordx4 v220, v[8:11], s[46:47]
	v_add_u32_e32 v220, 0x6000, v220
	s_waitcnt lgkmcnt(5)
	global_store_dwordx4 v220, v[12:15], s[46:47]
	v_add_u32_e32 v220, 0x6000, v220
	s_waitcnt lgkmcnt(4)
	global_store_dwordx4 v220, v[16:19], s[46:47]
	v_add_u32_e32 v220, 0x6000, v220
	s_waitcnt lgkmcnt(3)
	global_store_dwordx4 v220, v[20:23], s[46:47]
	v_add_u32_e32 v220, 0x6000, v220
	s_waitcnt lgkmcnt(2)
	global_store_dwordx4 v220, v[24:27], s[46:47]
	v_add_u32_e32 v220, 0x6000, v220
	s_waitcnt lgkmcnt(1)
	global_store_dwordx4 v220, v[28:31], s[46:47]
	v_add_u32_e32 v220, 0x6000, v220
	s_waitcnt lgkmcnt(0)
	global_store_dwordx4 v220, v[32:35], s[46:47]
	s_barrier
	s_add_u32 s46, s48, 0x1031c000
	s_addc_u32 s47, s49, 0
	s_add_u32 s46, s46, s18
	s_addc_u32 s47, s47, 0
	s_add_u32 s46, s46, 0x100
	s_addc_u32 s47, s47, 0
	v_mul_f32_e32 v76, v76, v216
	v_mul_f32_e32 v77, v77, v216
	v_mul_f32_e32 v78, v78, v216
	v_mul_f32_e32 v79, v79, v216
	v_mul_f32_e32 v148, v148, v217
	v_mul_f32_e32 v149, v149, v217
	v_mul_f32_e32 v150, v150, v217
	v_mul_f32_e32 v151, v151, v217
	v_mul_f32_e32 v164, v164, v218
	v_mul_f32_e32 v165, v165, v218
	v_mul_f32_e32 v166, v166, v218
	v_mul_f32_e32 v167, v167, v218
	v_mul_f32_e32 v180, v180, v219
	v_mul_f32_e32 v181, v181, v219
	v_mul_f32_e32 v182, v182, v219
	v_mul_f32_e32 v183, v183, v219
	s_add_i32 s0, s19, 8
	s_mul_hi_u32 s1, s0, 0x2aaaaaab
	s_mul_i32 s1, s1, 6
	s_sub_i32 s0, s0, s1
	s_cmp_lt_u32 s0, 4
	s_cbranch_scc1 .Luq_nr1_0
	s_cmp_lg_u32 s27, 0
	s_cbranch_scc1 .Luq_nr1_0
	s_cmp_eq_u32 s0, 5
	s_cbranch_scc1 .Luq_h11_0
	v_mov_b32_e32 v240, v236
	v_mov_b32_e32 v241, v236
	v_mov_b32_e32 v242, v236
	v_mov_b32_e32 v243, v236
	s_branch .Luq_rp1_0

.Luq_rp1_0:
	v_mul_f32_e32 v244, v232, v240
	v_mul_f32_e32 v245, v233, v240
	v_mul_f32_e32 v244, 0.15915494, v244
	v_mul_f32_e32 v245, 0.15915494, v245
	v_mov_b32_e32 v250, v76
	v_mov_b32_e32 v251, v77
	v_mov_b32_e32 v252, v76
	v_mov_b32_e32 v253, v77
	v_sin_f32_e32 v246, v244
	v_sin_f32_e32 v247, v245
	v_cos_f32_e32 v248, v244
	v_cos_f32_e32 v249, v245
	v_permlane32_swap_b32_e32 v250, v252
	v_permlane32_swap_b32_e32 v251, v253
	v_cndmask_b32_e64 v244, v248, -v246, s[50:51]
	v_cndmask_b32_e64 v245, v249, -v247, s[50:51]
	v_cndmask_b32_e64 v246, v246, v248, s[50:51]
	v_cndmask_b32_e64 v247, v247, v249, s[50:51]
	v_mul_f32_e32 v254, v252, v244
	v_mul_f32_e32 v255, v253, v245
	v_fma_f32 v76, v250, v246, v254
	v_fma_f32 v77, v251, v247, v255
	v_mul_f32_e32 v244, v234, v240
	v_mul_f32_e32 v245, v235, v240
	v_mul_f32_e32 v244, 0.15915494, v244
	v_mul_f32_e32 v245, 0.15915494, v245
	v_mov_b32_e32 v250, v78
	v_mov_b32_e32 v251, v79
	v_mov_b32_e32 v252, v78
	v_mov_b32_e32 v253, v79
	v_sin_f32_e32 v246, v244
	v_sin_f32_e32 v247, v245
	v_cos_f32_e32 v248, v244
	v_cos_f32_e32 v249, v245
	v_permlane32_swap_b32_e32 v250, v252
	v_permlane32_swap_b32_e32 v251, v253
	v_cndmask_b32_e64 v244, v248, -v246, s[50:51]
	v_cndmask_b32_e64 v245, v249, -v247, s[50:51]
	v_cndmask_b32_e64 v246, v246, v248, s[50:51]
	v_cndmask_b32_e64 v247, v247, v249, s[50:51]
	v_mul_f32_e32 v254, v252, v244
	v_mul_f32_e32 v255, v253, v245
	v_fma_f32 v78, v250, v246, v254
	v_fma_f32 v79, v251, v247, v255
	v_mul_f32_e32 v244, v232, v241
	v_mul_f32_e32 v245, v233, v241
	v_mul_f32_e32 v244, 0.15915494, v244
	v_mul_f32_e32 v245, 0.15915494, v245
	v_mov_b32_e32 v250, v148
	v_mov_b32_e32 v251, v149
	v_mov_b32_e32 v252, v148
	v_mov_b32_e32 v253, v149
	v_sin_f32_e32 v246, v244
	v_sin_f32_e32 v247, v245
	v_cos_f32_e32 v248, v244
	v_cos_f32_e32 v249, v245
	v_permlane32_swap_b32_e32 v250, v252
	v_permlane32_swap_b32_e32 v251, v253
	v_cndmask_b32_e64 v244, v248, -v246, s[50:51]
	v_cndmask_b32_e64 v245, v249, -v247, s[50:51]
	v_cndmask_b32_e64 v246, v246, v248, s[50:51]
	v_cndmask_b32_e64 v247, v247, v249, s[50:51]
	v_mul_f32_e32 v254, v252, v244
	v_mul_f32_e32 v255, v253, v245
	v_fma_f32 v148, v250, v246, v254
	v_fma_f32 v149, v251, v247, v255
	v_mul_f32_e32 v244, v234, v241
	v_mul_f32_e32 v245, v235, v241
	v_mul_f32_e32 v244, 0.15915494, v244
	v_mul_f32_e32 v245, 0.15915494, v245
	v_mov_b32_e32 v250, v150
	v_mov_b32_e32 v251, v151
	v_mov_b32_e32 v252, v150
	v_mov_b32_e32 v253, v151
	v_sin_f32_e32 v246, v244
	v_sin_f32_e32 v247, v245
	v_cos_f32_e32 v248, v244
	v_cos_f32_e32 v249, v245
	v_permlane32_swap_b32_e32 v250, v252
	v_permlane32_swap_b32_e32 v251, v253
	v_cndmask_b32_e64 v244, v248, -v246, s[50:51]
	v_cndmask_b32_e64 v245, v249, -v247, s[50:51]
	v_cndmask_b32_e64 v246, v246, v248, s[50:51]
	v_cndmask_b32_e64 v247, v247, v249, s[50:51]
	v_mul_f32_e32 v254, v252, v244
	v_mul_f32_e32 v255, v253, v245
	v_fma_f32 v150, v250, v246, v254
	v_fma_f32 v151, v251, v247, v255
	v_mul_f32_e32 v244, v232, v242
	v_mul_f32_e32 v245, v233, v242
	v_mul_f32_e32 v244, 0.15915494, v244
	v_mul_f32_e32 v245, 0.15915494, v245
	v_mov_b32_e32 v250, v164
	v_mov_b32_e32 v251, v165
	v_mov_b32_e32 v252, v164
	v_mov_b32_e32 v253, v165
	v_sin_f32_e32 v246, v244
	v_sin_f32_e32 v247, v245
	v_cos_f32_e32 v248, v244
	v_cos_f32_e32 v249, v245
	v_permlane32_swap_b32_e32 v250, v252
	v_permlane32_swap_b32_e32 v251, v253
	v_cndmask_b32_e64 v244, v248, -v246, s[50:51]
	v_cndmask_b32_e64 v245, v249, -v247, s[50:51]
	v_cndmask_b32_e64 v246, v246, v248, s[50:51]
	v_cndmask_b32_e64 v247, v247, v249, s[50:51]
	v_mul_f32_e32 v254, v252, v244
	v_mul_f32_e32 v255, v253, v245
	v_fma_f32 v164, v250, v246, v254
	v_fma_f32 v165, v251, v247, v255
	v_mul_f32_e32 v244, v234, v242
	v_mul_f32_e32 v245, v235, v242
	v_mul_f32_e32 v244, 0.15915494, v244
	v_mul_f32_e32 v245, 0.15915494, v245
	v_mov_b32_e32 v250, v166
	v_mov_b32_e32 v251, v167
	v_mov_b32_e32 v252, v166
	v_mov_b32_e32 v253, v167
	v_sin_f32_e32 v246, v244
	v_sin_f32_e32 v247, v245
	v_cos_f32_e32 v248, v244
	v_cos_f32_e32 v249, v245
	v_permlane32_swap_b32_e32 v250, v252
	v_permlane32_swap_b32_e32 v251, v253
	v_cndmask_b32_e64 v244, v248, -v246, s[50:51]
	v_cndmask_b32_e64 v245, v249, -v247, s[50:51]
	v_cndmask_b32_e64 v246, v246, v248, s[50:51]
	v_cndmask_b32_e64 v247, v247, v249, s[50:51]
	v_mul_f32_e32 v254, v252, v244
	v_mul_f32_e32 v255, v253, v245
	v_fma_f32 v166, v250, v246, v254
	v_fma_f32 v167, v251, v247, v255
	v_mul_f32_e32 v244, v232, v243
	v_mul_f32_e32 v245, v233, v243
	v_mul_f32_e32 v244, 0.15915494, v244
	v_mul_f32_e32 v245, 0.15915494, v245
	v_mov_b32_e32 v250, v180
	v_mov_b32_e32 v251, v181
	v_mov_b32_e32 v252, v180
	v_mov_b32_e32 v253, v181
	v_sin_f32_e32 v246, v244
	v_sin_f32_e32 v247, v245
	v_cos_f32_e32 v248, v244
	v_cos_f32_e32 v249, v245
	v_permlane32_swap_b32_e32 v250, v252
	v_permlane32_swap_b32_e32 v251, v253
	v_cndmask_b32_e64 v244, v248, -v246, s[50:51]
	v_cndmask_b32_e64 v245, v249, -v247, s[50:51]
	v_cndmask_b32_e64 v246, v246, v248, s[50:51]
	v_cndmask_b32_e64 v247, v247, v249, s[50:51]
	v_mul_f32_e32 v254, v252, v244
	v_mul_f32_e32 v255, v253, v245
	v_fma_f32 v180, v250, v246, v254
	v_fma_f32 v181, v251, v247, v255
	v_mul_f32_e32 v244, v234, v243
	v_mul_f32_e32 v245, v235, v243
	v_mul_f32_e32 v244, 0.15915494, v244
	v_mul_f32_e32 v245, 0.15915494, v245
	v_mov_b32_e32 v250, v182
	v_mov_b32_e32 v251, v183
	v_mov_b32_e32 v252, v182
	v_mov_b32_e32 v253, v183
	v_sin_f32_e32 v246, v244
	v_sin_f32_e32 v247, v245
	v_cos_f32_e32 v248, v244
	v_cos_f32_e32 v249, v245
	v_permlane32_swap_b32_e32 v250, v252
	v_permlane32_swap_b32_e32 v251, v253
	v_cndmask_b32_e64 v244, v248, -v246, s[50:51]
	v_cndmask_b32_e64 v245, v249, -v247, s[50:51]
	v_cndmask_b32_e64 v246, v246, v248, s[50:51]
	v_cndmask_b32_e64 v247, v247, v249, s[50:51]
	v_mul_f32_e32 v254, v252, v244
	v_mul_f32_e32 v255, v253, v245
	v_fma_f32 v182, v250, v246, v254
	v_fma_f32 v183, v251, v247, v255
.Luq_nr1_0:
	v_cvt_pk_bf16_f32 v2, v76, v77
	v_cvt_pk_bf16_f32 v3, v78, v79
	ds_write_b64 v213, v[2:3] offset:0
	v_cvt_pk_bf16_f32 v214, v148, v149
	v_cvt_pk_bf16_f32 v215, v150, v151
	ds_write_b64 v213, v[214:215] offset:4352
	v_cvt_pk_bf16_f32 v2, v164, v165
	v_cvt_pk_bf16_f32 v3, v166, v167
	ds_write_b64 v213, v[2:3] offset:8704
	v_cvt_pk_bf16_f32 v214, v180, v181
	v_cvt_pk_bf16_f32 v215, v182, v183
	ds_write_b64 v213, v[214:215] offset:13056
	v_mul_f32_e32 v80, v80, v216
	v_mul_f32_e32 v81, v81, v216
	v_mul_f32_e32 v82, v82, v216
	v_mul_f32_e32 v83, v83, v216
	v_mul_f32_e32 v152, v152, v217
	v_mul_f32_e32 v153, v153, v217
	v_mul_f32_e32 v154, v154, v217
	v_mul_f32_e32 v155, v155, v217
	v_mul_f32_e32 v168, v168, v218
	v_mul_f32_e32 v169, v169, v218
	v_mul_f32_e32 v170, v170, v218
	v_mul_f32_e32 v171, v171, v218
	v_mul_f32_e32 v184, v184, v219
	v_mul_f32_e32 v185, v185, v219
	v_mul_f32_e32 v186, v186, v219
	v_mul_f32_e32 v187, v187, v219
	s_add_i32 s0, s19, 9
	s_mul_hi_u32 s1, s0, 0x2aaaaaab
	s_mul_i32 s1, s1, 6
	s_sub_i32 s0, s0, s1
	s_cmp_lt_u32 s0, 4
	s_cbranch_scc1 .Luq_nr1_1
	s_cmp_lg_u32 s27, 0
	s_cbranch_scc1 .Luq_nr1_1
	s_cmp_eq_u32 s0, 5
	s_cbranch_scc1 .Luq_h11_1
	v_mov_b32_e32 v240, v236
	v_mov_b32_e32 v241, v236
	v_mov_b32_e32 v242, v236
	v_mov_b32_e32 v243, v236
	s_branch .Luq_rp1_1

.Luq_rp1_1:
	v_mul_f32_e32 v244, v232, v240
	v_mul_f32_e32 v245, v233, v240
	v_mul_f32_e32 v244, 0.15915494, v244
	v_mul_f32_e32 v245, 0.15915494, v245
	v_mov_b32_e32 v250, v80
	v_mov_b32_e32 v251, v81
	v_mov_b32_e32 v252, v80
	v_mov_b32_e32 v253, v81
	v_sin_f32_e32 v246, v244
	v_sin_f32_e32 v247, v245
	v_cos_f32_e32 v248, v244
	v_cos_f32_e32 v249, v245
	v_permlane32_swap_b32_e32 v250, v252
	v_permlane32_swap_b32_e32 v251, v253
	v_cndmask_b32_e64 v244, v248, -v246, s[50:51]
	v_cndmask_b32_e64 v245, v249, -v247, s[50:51]
	v_cndmask_b32_e64 v246, v246, v248, s[50:51]
	v_cndmask_b32_e64 v247, v247, v249, s[50:51]
	v_mul_f32_e32 v254, v252, v244
	v_mul_f32_e32 v255, v253, v245
	v_fma_f32 v80, v250, v246, v254
	v_fma_f32 v81, v251, v247, v255
	v_mul_f32_e32 v244, v234, v240
	v_mul_f32_e32 v245, v235, v240
	v_mul_f32_e32 v244, 0.15915494, v244
	v_mul_f32_e32 v245, 0.15915494, v245
	v_mov_b32_e32 v250, v82
	v_mov_b32_e32 v251, v83
	v_mov_b32_e32 v252, v82
	v_mov_b32_e32 v253, v83
	v_sin_f32_e32 v246, v244
	v_sin_f32_e32 v247, v245
	v_cos_f32_e32 v248, v244
	v_cos_f32_e32 v249, v245
	v_permlane32_swap_b32_e32 v250, v252
	v_permlane32_swap_b32_e32 v251, v253
	v_cndmask_b32_e64 v244, v248, -v246, s[50:51]
	v_cndmask_b32_e64 v245, v249, -v247, s[50:51]
	v_cndmask_b32_e64 v246, v246, v248, s[50:51]
	v_cndmask_b32_e64 v247, v247, v249, s[50:51]
	v_mul_f32_e32 v254, v252, v244
	v_mul_f32_e32 v255, v253, v245
	v_fma_f32 v82, v250, v246, v254
	v_fma_f32 v83, v251, v247, v255
	v_mul_f32_e32 v244, v232, v241
	v_mul_f32_e32 v245, v233, v241
	v_mul_f32_e32 v244, 0.15915494, v244
	v_mul_f32_e32 v245, 0.15915494, v245
	v_mov_b32_e32 v250, v152
	v_mov_b32_e32 v251, v153
	v_mov_b32_e32 v252, v152
	v_mov_b32_e32 v253, v153
	v_sin_f32_e32 v246, v244
	v_sin_f32_e32 v247, v245
	v_cos_f32_e32 v248, v244
	v_cos_f32_e32 v249, v245
	v_permlane32_swap_b32_e32 v250, v252
	v_permlane32_swap_b32_e32 v251, v253
	v_cndmask_b32_e64 v244, v248, -v246, s[50:51]
	v_cndmask_b32_e64 v245, v249, -v247, s[50:51]
	v_cndmask_b32_e64 v246, v246, v248, s[50:51]
	v_cndmask_b32_e64 v247, v247, v249, s[50:51]
	v_mul_f32_e32 v254, v252, v244
	v_mul_f32_e32 v255, v253, v245
	v_fma_f32 v152, v250, v246, v254
	v_fma_f32 v153, v251, v247, v255
	v_mul_f32_e32 v244, v234, v241
	v_mul_f32_e32 v245, v235, v241
	v_mul_f32_e32 v244, 0.15915494, v244
	v_mul_f32_e32 v245, 0.15915494, v245
	v_mov_b32_e32 v250, v154
	v_mov_b32_e32 v251, v155
	v_mov_b32_e32 v252, v154
	v_mov_b32_e32 v253, v155
	v_sin_f32_e32 v246, v244
	v_sin_f32_e32 v247, v245
	v_cos_f32_e32 v248, v244
	v_cos_f32_e32 v249, v245
	v_permlane32_swap_b32_e32 v250, v252
	v_permlane32_swap_b32_e32 v251, v253
	v_cndmask_b32_e64 v244, v248, -v246, s[50:51]
	v_cndmask_b32_e64 v245, v249, -v247, s[50:51]
	v_cndmask_b32_e64 v246, v246, v248, s[50:51]
	v_cndmask_b32_e64 v247, v247, v249, s[50:51]
	v_mul_f32_e32 v254, v252, v244
	v_mul_f32_e32 v255, v253, v245
	v_fma_f32 v154, v250, v246, v254
	v_fma_f32 v155, v251, v247, v255
	v_mul_f32_e32 v244, v232, v242
	v_mul_f32_e32 v245, v233, v242
	v_mul_f32_e32 v244, 0.15915494, v244
	v_mul_f32_e32 v245, 0.15915494, v245
	v_mov_b32_e32 v250, v168
	v_mov_b32_e32 v251, v169
	v_mov_b32_e32 v252, v168
	v_mov_b32_e32 v253, v169
	v_sin_f32_e32 v246, v244
	v_sin_f32_e32 v247, v245
	v_cos_f32_e32 v248, v244
	v_cos_f32_e32 v249, v245
	v_permlane32_swap_b32_e32 v250, v252
	v_permlane32_swap_b32_e32 v251, v253
	v_cndmask_b32_e64 v244, v248, -v246, s[50:51]
	v_cndmask_b32_e64 v245, v249, -v247, s[50:51]
	v_cndmask_b32_e64 v246, v246, v248, s[50:51]
	v_cndmask_b32_e64 v247, v247, v249, s[50:51]
	v_mul_f32_e32 v254, v252, v244
	v_mul_f32_e32 v255, v253, v245
	v_fma_f32 v168, v250, v246, v254
	v_fma_f32 v169, v251, v247, v255
	v_mul_f32_e32 v244, v234, v242
	v_mul_f32_e32 v245, v235, v242
	v_mul_f32_e32 v244, 0.15915494, v244
	v_mul_f32_e32 v245, 0.15915494, v245
	v_mov_b32_e32 v250, v170
	v_mov_b32_e32 v251, v171
	v_mov_b32_e32 v252, v170
	v_mov_b32_e32 v253, v171
	v_sin_f32_e32 v246, v244
	v_sin_f32_e32 v247, v245
	v_cos_f32_e32 v248, v244
	v_cos_f32_e32 v249, v245
	v_permlane32_swap_b32_e32 v250, v252
	v_permlane32_swap_b32_e32 v251, v253
	v_cndmask_b32_e64 v244, v248, -v246, s[50:51]
	v_cndmask_b32_e64 v245, v249, -v247, s[50:51]
	v_cndmask_b32_e64 v246, v246, v248, s[50:51]
	v_cndmask_b32_e64 v247, v247, v249, s[50:51]
	v_mul_f32_e32 v254, v252, v244
	v_mul_f32_e32 v255, v253, v245
	v_fma_f32 v170, v250, v246, v254
	v_fma_f32 v171, v251, v247, v255
	v_mul_f32_e32 v244, v232, v243
	v_mul_f32_e32 v245, v233, v243
	v_mul_f32_e32 v244, 0.15915494, v244
	v_mul_f32_e32 v245, 0.15915494, v245
	v_mov_b32_e32 v250, v184
	v_mov_b32_e32 v251, v185
	v_mov_b32_e32 v252, v184
	v_mov_b32_e32 v253, v185
	v_sin_f32_e32 v246, v244
	v_sin_f32_e32 v247, v245
	v_cos_f32_e32 v248, v244
	v_cos_f32_e32 v249, v245
	v_permlane32_swap_b32_e32 v250, v252
	v_permlane32_swap_b32_e32 v251, v253
	v_cndmask_b32_e64 v244, v248, -v246, s[50:51]
	v_cndmask_b32_e64 v245, v249, -v247, s[50:51]
	v_cndmask_b32_e64 v246, v246, v248, s[50:51]
	v_cndmask_b32_e64 v247, v247, v249, s[50:51]
	v_mul_f32_e32 v254, v252, v244
	v_mul_f32_e32 v255, v253, v245
	v_fma_f32 v184, v250, v246, v254
	v_fma_f32 v185, v251, v247, v255
	v_mul_f32_e32 v244, v234, v243
	v_mul_f32_e32 v245, v235, v243
	v_mul_f32_e32 v244, 0.15915494, v244
	v_mul_f32_e32 v245, 0.15915494, v245
	v_mov_b32_e32 v250, v186
	v_mov_b32_e32 v251, v187
	v_mov_b32_e32 v252, v186
	v_mov_b32_e32 v253, v187
	v_sin_f32_e32 v246, v244
	v_sin_f32_e32 v247, v245
	v_cos_f32_e32 v248, v244
	v_cos_f32_e32 v249, v245
	v_permlane32_swap_b32_e32 v250, v252
	v_permlane32_swap_b32_e32 v251, v253
	v_cndmask_b32_e64 v244, v248, -v246, s[50:51]
	v_cndmask_b32_e64 v245, v249, -v247, s[50:51]
	v_cndmask_b32_e64 v246, v246, v248, s[50:51]
	v_cndmask_b32_e64 v247, v247, v249, s[50:51]
	v_mul_f32_e32 v254, v252, v244
	v_mul_f32_e32 v255, v253, v245
	v_fma_f32 v186, v250, v246, v254
	v_fma_f32 v187, v251, v247, v255
.Luq_nr1_1:
	v_cvt_pk_bf16_f32 v2, v80, v81
	v_cvt_pk_bf16_f32 v3, v82, v83
	ds_write_b64 v213, v[2:3] offset:32
	v_cvt_pk_bf16_f32 v214, v152, v153
	v_cvt_pk_bf16_f32 v215, v154, v155
	ds_write_b64 v213, v[214:215] offset:4384
	v_cvt_pk_bf16_f32 v2, v168, v169
	v_cvt_pk_bf16_f32 v3, v170, v171
	ds_write_b64 v213, v[2:3] offset:8736
	v_cvt_pk_bf16_f32 v214, v184, v185
	v_cvt_pk_bf16_f32 v215, v186, v187
	ds_write_b64 v213, v[214:215] offset:13088
	v_mul_f32_e32 v84, v84, v216
	v_mul_f32_e32 v85, v85, v216
	v_mul_f32_e32 v86, v86, v216
	v_mul_f32_e32 v87, v87, v216
	v_mul_f32_e32 v156, v156, v217
	v_mul_f32_e32 v157, v157, v217
	v_mul_f32_e32 v158, v158, v217
	v_mul_f32_e32 v159, v159, v217
	v_mul_f32_e32 v172, v172, v218
	v_mul_f32_e32 v173, v173, v218
	v_mul_f32_e32 v174, v174, v218
	v_mul_f32_e32 v175, v175, v218
	v_mul_f32_e32 v188, v188, v219
	v_mul_f32_e32 v189, v189, v219
	v_mul_f32_e32 v190, v190, v219
	v_mul_f32_e32 v191, v191, v219
	s_add_i32 s0, s19, 10
	s_mul_hi_u32 s1, s0, 0x2aaaaaab
	s_mul_i32 s1, s1, 6
	s_sub_i32 s0, s0, s1
	s_cmp_lt_u32 s0, 4
	s_cbranch_scc1 .Luq_nr1_2
	s_cmp_lg_u32 s27, 0
	s_cbranch_scc1 .Luq_nr1_2
	s_cmp_eq_u32 s0, 5
	s_cbranch_scc1 .Luq_h11_2
	v_mov_b32_e32 v240, v236
	v_mov_b32_e32 v241, v236
	v_mov_b32_e32 v242, v236
	v_mov_b32_e32 v243, v236
	s_branch .Luq_rp1_2

.Luq_rp1_2:
	v_mul_f32_e32 v244, v232, v240
	v_mul_f32_e32 v245, v233, v240
	v_mul_f32_e32 v244, 0.15915494, v244
	v_mul_f32_e32 v245, 0.15915494, v245
	v_mov_b32_e32 v250, v84
	v_mov_b32_e32 v251, v85
	v_mov_b32_e32 v252, v84
	v_mov_b32_e32 v253, v85
	v_sin_f32_e32 v246, v244
	v_sin_f32_e32 v247, v245
	v_cos_f32_e32 v248, v244
	v_cos_f32_e32 v249, v245
	v_permlane32_swap_b32_e32 v250, v252
	v_permlane32_swap_b32_e32 v251, v253
	v_cndmask_b32_e64 v244, v248, -v246, s[50:51]
	v_cndmask_b32_e64 v245, v249, -v247, s[50:51]
	v_cndmask_b32_e64 v246, v246, v248, s[50:51]
	v_cndmask_b32_e64 v247, v247, v249, s[50:51]
	v_mul_f32_e32 v254, v252, v244
	v_mul_f32_e32 v255, v253, v245
	v_fma_f32 v84, v250, v246, v254
	v_fma_f32 v85, v251, v247, v255
	v_mul_f32_e32 v244, v234, v240
	v_mul_f32_e32 v245, v235, v240
	v_mul_f32_e32 v244, 0.15915494, v244
	v_mul_f32_e32 v245, 0.15915494, v245
	v_mov_b32_e32 v250, v86
	v_mov_b32_e32 v251, v87
	v_mov_b32_e32 v252, v86
	v_mov_b32_e32 v253, v87
	v_sin_f32_e32 v246, v244
	v_sin_f32_e32 v247, v245
	v_cos_f32_e32 v248, v244
	v_cos_f32_e32 v249, v245
	v_permlane32_swap_b32_e32 v250, v252
	v_permlane32_swap_b32_e32 v251, v253
	v_cndmask_b32_e64 v244, v248, -v246, s[50:51]
	v_cndmask_b32_e64 v245, v249, -v247, s[50:51]
	v_cndmask_b32_e64 v246, v246, v248, s[50:51]
	v_cndmask_b32_e64 v247, v247, v249, s[50:51]
	v_mul_f32_e32 v254, v252, v244
	v_mul_f32_e32 v255, v253, v245
	v_fma_f32 v86, v250, v246, v254
	v_fma_f32 v87, v251, v247, v255
	v_mul_f32_e32 v244, v232, v241
	v_mul_f32_e32 v245, v233, v241
	v_mul_f32_e32 v244, 0.15915494, v244
	v_mul_f32_e32 v245, 0.15915494, v245
	v_mov_b32_e32 v250, v156
	v_mov_b32_e32 v251, v157
	v_mov_b32_e32 v252, v156
	v_mov_b32_e32 v253, v157
	v_sin_f32_e32 v246, v244
	v_sin_f32_e32 v247, v245
	v_cos_f32_e32 v248, v244
	v_cos_f32_e32 v249, v245
	v_permlane32_swap_b32_e32 v250, v252
	v_permlane32_swap_b32_e32 v251, v253
	v_cndmask_b32_e64 v244, v248, -v246, s[50:51]
	v_cndmask_b32_e64 v245, v249, -v247, s[50:51]
	v_cndmask_b32_e64 v246, v246, v248, s[50:51]
	v_cndmask_b32_e64 v247, v247, v249, s[50:51]
	v_mul_f32_e32 v254, v252, v244
	v_mul_f32_e32 v255, v253, v245
	v_fma_f32 v156, v250, v246, v254
	v_fma_f32 v157, v251, v247, v255
	v_mul_f32_e32 v244, v234, v241
	v_mul_f32_e32 v245, v235, v241
	v_mul_f32_e32 v244, 0.15915494, v244
	v_mul_f32_e32 v245, 0.15915494, v245
	v_mov_b32_e32 v250, v158
	v_mov_b32_e32 v251, v159
	v_mov_b32_e32 v252, v158
	v_mov_b32_e32 v253, v159
	v_sin_f32_e32 v246, v244
	v_sin_f32_e32 v247, v245
	v_cos_f32_e32 v248, v244
	v_cos_f32_e32 v249, v245
	v_permlane32_swap_b32_e32 v250, v252
	v_permlane32_swap_b32_e32 v251, v253
	v_cndmask_b32_e64 v244, v248, -v246, s[50:51]
	v_cndmask_b32_e64 v245, v249, -v247, s[50:51]
	v_cndmask_b32_e64 v246, v246, v248, s[50:51]
	v_cndmask_b32_e64 v247, v247, v249, s[50:51]
	v_mul_f32_e32 v254, v252, v244
	v_mul_f32_e32 v255, v253, v245
	v_fma_f32 v158, v250, v246, v254
	v_fma_f32 v159, v251, v247, v255
	v_mul_f32_e32 v244, v232, v242
	v_mul_f32_e32 v245, v233, v242
	v_mul_f32_e32 v244, 0.15915494, v244
	v_mul_f32_e32 v245, 0.15915494, v245
	v_mov_b32_e32 v250, v172
	v_mov_b32_e32 v251, v173
	v_mov_b32_e32 v252, v172
	v_mov_b32_e32 v253, v173
	v_sin_f32_e32 v246, v244
	v_sin_f32_e32 v247, v245
	v_cos_f32_e32 v248, v244
	v_cos_f32_e32 v249, v245
	v_permlane32_swap_b32_e32 v250, v252
	v_permlane32_swap_b32_e32 v251, v253
	v_cndmask_b32_e64 v244, v248, -v246, s[50:51]
	v_cndmask_b32_e64 v245, v249, -v247, s[50:51]
	v_cndmask_b32_e64 v246, v246, v248, s[50:51]
	v_cndmask_b32_e64 v247, v247, v249, s[50:51]
	v_mul_f32_e32 v254, v252, v244
	v_mul_f32_e32 v255, v253, v245
	v_fma_f32 v172, v250, v246, v254
	v_fma_f32 v173, v251, v247, v255
	v_mul_f32_e32 v244, v234, v242
	v_mul_f32_e32 v245, v235, v242
	v_mul_f32_e32 v244, 0.15915494, v244
	v_mul_f32_e32 v245, 0.15915494, v245
	v_mov_b32_e32 v250, v174
	v_mov_b32_e32 v251, v175
	v_mov_b32_e32 v252, v174
	v_mov_b32_e32 v253, v175
	v_sin_f32_e32 v246, v244
	v_sin_f32_e32 v247, v245
	v_cos_f32_e32 v248, v244
	v_cos_f32_e32 v249, v245
	v_permlane32_swap_b32_e32 v250, v252
	v_permlane32_swap_b32_e32 v251, v253
	v_cndmask_b32_e64 v244, v248, -v246, s[50:51]
	v_cndmask_b32_e64 v245, v249, -v247, s[50:51]
	v_cndmask_b32_e64 v246, v246, v248, s[50:51]
	v_cndmask_b32_e64 v247, v247, v249, s[50:51]
	v_mul_f32_e32 v254, v252, v244
	v_mul_f32_e32 v255, v253, v245
	v_fma_f32 v174, v250, v246, v254
	v_fma_f32 v175, v251, v247, v255
	v_mul_f32_e32 v244, v232, v243
	v_mul_f32_e32 v245, v233, v243
	v_mul_f32_e32 v244, 0.15915494, v244
	v_mul_f32_e32 v245, 0.15915494, v245
	v_mov_b32_e32 v250, v188
	v_mov_b32_e32 v251, v189
	v_mov_b32_e32 v252, v188
	v_mov_b32_e32 v253, v189
	v_sin_f32_e32 v246, v244
	v_sin_f32_e32 v247, v245
	v_cos_f32_e32 v248, v244
	v_cos_f32_e32 v249, v245
	v_permlane32_swap_b32_e32 v250, v252
	v_permlane32_swap_b32_e32 v251, v253
	v_cndmask_b32_e64 v244, v248, -v246, s[50:51]
	v_cndmask_b32_e64 v245, v249, -v247, s[50:51]
	v_cndmask_b32_e64 v246, v246, v248, s[50:51]
	v_cndmask_b32_e64 v247, v247, v249, s[50:51]
	v_mul_f32_e32 v254, v252, v244
	v_mul_f32_e32 v255, v253, v245
	v_fma_f32 v188, v250, v246, v254
	v_fma_f32 v189, v251, v247, v255
	v_mul_f32_e32 v244, v234, v243
	v_mul_f32_e32 v245, v235, v243
	v_mul_f32_e32 v244, 0.15915494, v244
	v_mul_f32_e32 v245, 0.15915494, v245
	v_mov_b32_e32 v250, v190
	v_mov_b32_e32 v251, v191
	v_mov_b32_e32 v252, v190
	v_mov_b32_e32 v253, v191
	v_sin_f32_e32 v246, v244
	v_sin_f32_e32 v247, v245
	v_cos_f32_e32 v248, v244
	v_cos_f32_e32 v249, v245
	v_permlane32_swap_b32_e32 v250, v252
	v_permlane32_swap_b32_e32 v251, v253
	v_cndmask_b32_e64 v244, v248, -v246, s[50:51]
	v_cndmask_b32_e64 v245, v249, -v247, s[50:51]
	v_cndmask_b32_e64 v246, v246, v248, s[50:51]
	v_cndmask_b32_e64 v247, v247, v249, s[50:51]
	v_mul_f32_e32 v254, v252, v244
	v_mul_f32_e32 v255, v253, v245
	v_fma_f32 v190, v250, v246, v254
	v_fma_f32 v191, v251, v247, v255
.Luq_nr1_2:
	v_cvt_pk_bf16_f32 v2, v84, v85
	v_cvt_pk_bf16_f32 v3, v86, v87
	ds_write_b64 v213, v[2:3] offset:64
	v_cvt_pk_bf16_f32 v214, v156, v157
	v_cvt_pk_bf16_f32 v215, v158, v159
	ds_write_b64 v213, v[214:215] offset:4416
	v_cvt_pk_bf16_f32 v2, v172, v173
	v_cvt_pk_bf16_f32 v3, v174, v175
	ds_write_b64 v213, v[2:3] offset:8768
	v_cvt_pk_bf16_f32 v214, v188, v189
	v_cvt_pk_bf16_f32 v215, v190, v191
	ds_write_b64 v213, v[214:215] offset:13120
	v_mul_f32_e32 v144, v144, v216
	v_mul_f32_e32 v145, v145, v216
	v_mul_f32_e32 v146, v146, v216
	v_mul_f32_e32 v147, v147, v216
	v_mul_f32_e32 v160, v160, v217
	v_mul_f32_e32 v161, v161, v217
	v_mul_f32_e32 v162, v162, v217
	v_mul_f32_e32 v163, v163, v217
	v_mul_f32_e32 v176, v176, v218
	v_mul_f32_e32 v177, v177, v218
	v_mul_f32_e32 v178, v178, v218
	v_mul_f32_e32 v179, v179, v218
	v_mul_f32_e32 v192, v192, v219
	v_mul_f32_e32 v193, v193, v219
	v_mul_f32_e32 v194, v194, v219
	v_mul_f32_e32 v195, v195, v219
	s_add_i32 s0, s19, 11
	s_mul_hi_u32 s1, s0, 0x2aaaaaab
	s_mul_i32 s1, s1, 6
	s_sub_i32 s0, s0, s1
	s_cmp_lt_u32 s0, 4
	s_cbranch_scc1 .Luq_nr1_3
	s_cmp_lg_u32 s27, 0
	s_cbranch_scc1 .Luq_nr1_3
	s_cmp_eq_u32 s0, 5
	s_cbranch_scc1 .Luq_h11_3
	v_mov_b32_e32 v240, v236
	v_mov_b32_e32 v241, v236
	v_mov_b32_e32 v242, v236
	v_mov_b32_e32 v243, v236
	s_branch .Luq_rp1_3

.Luq_rp1_3:
	v_mul_f32_e32 v244, v232, v240
	v_mul_f32_e32 v245, v233, v240
	v_mul_f32_e32 v244, 0.15915494, v244
	v_mul_f32_e32 v245, 0.15915494, v245
	v_mov_b32_e32 v250, v144
	v_mov_b32_e32 v251, v145
	v_mov_b32_e32 v252, v144
	v_mov_b32_e32 v253, v145
	v_sin_f32_e32 v246, v244
	v_sin_f32_e32 v247, v245
	v_cos_f32_e32 v248, v244
	v_cos_f32_e32 v249, v245
	v_permlane32_swap_b32_e32 v250, v252
	v_permlane32_swap_b32_e32 v251, v253
	v_cndmask_b32_e64 v244, v248, -v246, s[50:51]
	v_cndmask_b32_e64 v245, v249, -v247, s[50:51]
	v_cndmask_b32_e64 v246, v246, v248, s[50:51]
	v_cndmask_b32_e64 v247, v247, v249, s[50:51]
	v_mul_f32_e32 v254, v252, v244
	v_mul_f32_e32 v255, v253, v245
	v_fma_f32 v144, v250, v246, v254
	v_fma_f32 v145, v251, v247, v255
	v_mul_f32_e32 v244, v234, v240
	v_mul_f32_e32 v245, v235, v240
	v_mul_f32_e32 v244, 0.15915494, v244
	v_mul_f32_e32 v245, 0.15915494, v245
	v_mov_b32_e32 v250, v146
	v_mov_b32_e32 v251, v147
	v_mov_b32_e32 v252, v146
	v_mov_b32_e32 v253, v147
	v_sin_f32_e32 v246, v244
	v_sin_f32_e32 v247, v245
	v_cos_f32_e32 v248, v244
	v_cos_f32_e32 v249, v245
	v_permlane32_swap_b32_e32 v250, v252
	v_permlane32_swap_b32_e32 v251, v253
	v_cndmask_b32_e64 v244, v248, -v246, s[50:51]
	v_cndmask_b32_e64 v245, v249, -v247, s[50:51]
	v_cndmask_b32_e64 v246, v246, v248, s[50:51]
	v_cndmask_b32_e64 v247, v247, v249, s[50:51]
	v_mul_f32_e32 v254, v252, v244
	v_mul_f32_e32 v255, v253, v245
	v_fma_f32 v146, v250, v246, v254
	v_fma_f32 v147, v251, v247, v255
	v_mul_f32_e32 v244, v232, v241
	v_mul_f32_e32 v245, v233, v241
	v_mul_f32_e32 v244, 0.15915494, v244
	v_mul_f32_e32 v245, 0.15915494, v245
	v_mov_b32_e32 v250, v160
	v_mov_b32_e32 v251, v161
	v_mov_b32_e32 v252, v160
	v_mov_b32_e32 v253, v161
	v_sin_f32_e32 v246, v244
	v_sin_f32_e32 v247, v245
	v_cos_f32_e32 v248, v244
	v_cos_f32_e32 v249, v245
	v_permlane32_swap_b32_e32 v250, v252
	v_permlane32_swap_b32_e32 v251, v253
	v_cndmask_b32_e64 v244, v248, -v246, s[50:51]
	v_cndmask_b32_e64 v245, v249, -v247, s[50:51]
	v_cndmask_b32_e64 v246, v246, v248, s[50:51]
	v_cndmask_b32_e64 v247, v247, v249, s[50:51]
	v_mul_f32_e32 v254, v252, v244
	v_mul_f32_e32 v255, v253, v245
	v_fma_f32 v160, v250, v246, v254
	v_fma_f32 v161, v251, v247, v255
	v_mul_f32_e32 v244, v234, v241
	v_mul_f32_e32 v245, v235, v241
	v_mul_f32_e32 v244, 0.15915494, v244
	v_mul_f32_e32 v245, 0.15915494, v245
	v_mov_b32_e32 v250, v162
	v_mov_b32_e32 v251, v163
	v_mov_b32_e32 v252, v162
	v_mov_b32_e32 v253, v163
	v_sin_f32_e32 v246, v244
	v_sin_f32_e32 v247, v245
	v_cos_f32_e32 v248, v244
	v_cos_f32_e32 v249, v245
	v_permlane32_swap_b32_e32 v250, v252
	v_permlane32_swap_b32_e32 v251, v253
	v_cndmask_b32_e64 v244, v248, -v246, s[50:51]
	v_cndmask_b32_e64 v245, v249, -v247, s[50:51]
	v_cndmask_b32_e64 v246, v246, v248, s[50:51]
	v_cndmask_b32_e64 v247, v247, v249, s[50:51]
	v_mul_f32_e32 v254, v252, v244
	v_mul_f32_e32 v255, v253, v245
	v_fma_f32 v162, v250, v246, v254
	v_fma_f32 v163, v251, v247, v255
	v_mul_f32_e32 v244, v232, v242
	v_mul_f32_e32 v245, v233, v242
	v_mul_f32_e32 v244, 0.15915494, v244
	v_mul_f32_e32 v245, 0.15915494, v245
	v_mov_b32_e32 v250, v176
	v_mov_b32_e32 v251, v177
	v_mov_b32_e32 v252, v176
	v_mov_b32_e32 v253, v177
	v_sin_f32_e32 v246, v244
	v_sin_f32_e32 v247, v245
	v_cos_f32_e32 v248, v244
	v_cos_f32_e32 v249, v245
	v_permlane32_swap_b32_e32 v250, v252
	v_permlane32_swap_b32_e32 v251, v253
	v_cndmask_b32_e64 v244, v248, -v246, s[50:51]
	v_cndmask_b32_e64 v245, v249, -v247, s[50:51]
	v_cndmask_b32_e64 v246, v246, v248, s[50:51]
	v_cndmask_b32_e64 v247, v247, v249, s[50:51]
	v_mul_f32_e32 v254, v252, v244
	v_mul_f32_e32 v255, v253, v245
	v_fma_f32 v176, v250, v246, v254
	v_fma_f32 v177, v251, v247, v255
	v_mul_f32_e32 v244, v234, v242
	v_mul_f32_e32 v245, v235, v242
	v_mul_f32_e32 v244, 0.15915494, v244
	v_mul_f32_e32 v245, 0.15915494, v245
	v_mov_b32_e32 v250, v178
	v_mov_b32_e32 v251, v179
	v_mov_b32_e32 v252, v178
	v_mov_b32_e32 v253, v179
	v_sin_f32_e32 v246, v244
	v_sin_f32_e32 v247, v245
	v_cos_f32_e32 v248, v244
	v_cos_f32_e32 v249, v245
	v_permlane32_swap_b32_e32 v250, v252
	v_permlane32_swap_b32_e32 v251, v253
	v_cndmask_b32_e64 v244, v248, -v246, s[50:51]
	v_cndmask_b32_e64 v245, v249, -v247, s[50:51]
	v_cndmask_b32_e64 v246, v246, v248, s[50:51]
	v_cndmask_b32_e64 v247, v247, v249, s[50:51]
	v_mul_f32_e32 v254, v252, v244
	v_mul_f32_e32 v255, v253, v245
	v_fma_f32 v178, v250, v246, v254
	v_fma_f32 v179, v251, v247, v255
	v_mul_f32_e32 v244, v232, v243
	v_mul_f32_e32 v245, v233, v243
	v_mul_f32_e32 v244, 0.15915494, v244
	v_mul_f32_e32 v245, 0.15915494, v245
	v_mov_b32_e32 v250, v192
	v_mov_b32_e32 v251, v193
	v_mov_b32_e32 v252, v192
	v_mov_b32_e32 v253, v193
	v_sin_f32_e32 v246, v244
	v_sin_f32_e32 v247, v245
	v_cos_f32_e32 v248, v244
	v_cos_f32_e32 v249, v245
	v_permlane32_swap_b32_e32 v250, v252
	v_permlane32_swap_b32_e32 v251, v253
	v_cndmask_b32_e64 v244, v248, -v246, s[50:51]
	v_cndmask_b32_e64 v245, v249, -v247, s[50:51]
	v_cndmask_b32_e64 v246, v246, v248, s[50:51]
	v_cndmask_b32_e64 v247, v247, v249, s[50:51]
	v_mul_f32_e32 v254, v252, v244
	v_mul_f32_e32 v255, v253, v245
	v_fma_f32 v192, v250, v246, v254
	v_fma_f32 v193, v251, v247, v255
	v_mul_f32_e32 v244, v234, v243
	v_mul_f32_e32 v245, v235, v243
	v_mul_f32_e32 v244, 0.15915494, v244
	v_mul_f32_e32 v245, 0.15915494, v245
	v_mov_b32_e32 v250, v194
	v_mov_b32_e32 v251, v195
	v_mov_b32_e32 v252, v194
	v_mov_b32_e32 v253, v195
	v_sin_f32_e32 v246, v244
	v_sin_f32_e32 v247, v245
	v_cos_f32_e32 v248, v244
	v_cos_f32_e32 v249, v245
	v_permlane32_swap_b32_e32 v250, v252
	v_permlane32_swap_b32_e32 v251, v253
	v_cndmask_b32_e64 v244, v248, -v246, s[50:51]
	v_cndmask_b32_e64 v245, v249, -v247, s[50:51]
	v_cndmask_b32_e64 v246, v246, v248, s[50:51]
	v_cndmask_b32_e64 v247, v247, v249, s[50:51]
	v_mul_f32_e32 v254, v252, v244
	v_mul_f32_e32 v255, v253, v245
	v_fma_f32 v194, v250, v246, v254
	v_fma_f32 v195, v251, v247, v255
.Luq_nr1_3:
	v_cvt_pk_bf16_f32 v2, v144, v145
	v_cvt_pk_bf16_f32 v3, v146, v147
	ds_write_b64 v213, v[2:3] offset:96
	v_cvt_pk_bf16_f32 v214, v160, v161
	v_cvt_pk_bf16_f32 v215, v162, v163
	ds_write_b64 v213, v[214:215] offset:4448
	v_cvt_pk_bf16_f32 v2, v176, v177
	v_cvt_pk_bf16_f32 v3, v178, v179
	ds_write_b64 v213, v[2:3] offset:8800
	v_cvt_pk_bf16_f32 v214, v192, v193
	v_cvt_pk_bf16_f32 v215, v194, v195
	ds_write_b64 v213, v[214:215] offset:13152
	s_waitcnt lgkmcnt(0)
	s_barrier
	ds_read_b128 v[4:7], v143 offset:0
	ds_read_b128 v[8:11], v143 offset:4352
	ds_read_b128 v[12:15], v143 offset:8704
	ds_read_b128 v[16:19], v143 offset:13056
	ds_read_b128 v[20:23], v143 offset:17408
	ds_read_b128 v[24:27], v143 offset:21760
	ds_read_b128 v[28:31], v143 offset:26112
	ds_read_b128 v[32:35], v143 offset:30464
	v_mov_b32_e32 v220, v71
	s_waitcnt lgkmcnt(7)
	global_store_dwordx4 v220, v[4:7], s[46:47]
	v_add_u32_e32 v220, 0x6000, v220
	s_waitcnt lgkmcnt(6)
	global_store_dwordx4 v220, v[8:11], s[46:47]
	v_add_u32_e32 v220, 0x6000, v220
	s_waitcnt lgkmcnt(5)
	global_store_dwordx4 v220, v[12:15], s[46:47]
	v_add_u32_e32 v220, 0x6000, v220
	s_waitcnt lgkmcnt(4)
	global_store_dwordx4 v220, v[16:19], s[46:47]
	v_add_u32_e32 v220, 0x6000, v220
	s_waitcnt lgkmcnt(3)
	global_store_dwordx4 v220, v[20:23], s[46:47]
	v_add_u32_e32 v220, 0x6000, v220
	s_waitcnt lgkmcnt(2)
	global_store_dwordx4 v220, v[24:27], s[46:47]
	v_add_u32_e32 v220, 0x6000, v220
	s_waitcnt lgkmcnt(1)
	global_store_dwordx4 v220, v[28:31], s[46:47]
	v_add_u32_e32 v220, 0x6000, v220
	s_waitcnt lgkmcnt(0)
	global_store_dwordx4 v220, v[32:35], s[46:47]
	s_barrier
	s_branch .LBB0_314
